# EpiResid epilogues of W_out and cross_wo projections: residual-row loads prefetched two iterations ahead so waits no longer include previous stores
# speedup vs baseline: 1.0038x; 1.0038x over previous
;     __device__ __forceinline__ void operator()(Acc& acc, const Unit& u, int wr, int wc, int fr, int fq, LAS unsigned char* lds) const {
;         const int col0 = u.pn * BM + wc * 32 + 4 * fq;
;         if (STp) row_stats_table(lds, STp, u.pm);
;         const LAS f32x2* SL = (const LAS f32x2*)(lds + SL_OFF);
;         f32x4 gg[2][2], bb[2][2];
;         if (STp) {
; #pragma unroll
;             for (int bj = 0; bj < 2; ++bj)
; #pragma unroll
;                 for (int n = 0; n < 2; ++n) { gg[bj][n] = *(const GASP f32x4*)(gam + col0 + bj * HALF + n * 16); bb[bj][n] = *(const GASP f32x4*)(bet + col0 + bj * HALF + n * 16); }
;         }
; #pragma unroll
;         for (int ai = 0; ai < 2; ++ai)
; #pragma unroll
;             for (int m = 0; m < 4; ++m) {
;                 const int rl = ai * HALF + wr * 64 + m * 16 + fr, row = u.pm * BM + rl;
;                 const float* rp = (row < split) ? res0 + (size_t)row * D : res1 + (size_t)(row - split) * D;
;                 float* op = out + (size_t)row * D;
;                 f32x2 st = (f32x2){0.f, 1.f}; if (STp) st = SL[rl];
;                 float s = 0.f, q = 0.f;
; #pragma unroll
;                 for (int bj = 0; bj < 2; ++bj)
; #pragma unroll
;                     for (int n = 0; n < 2; ++n) { const int c = col0 + bj * HALF + n * 16; f32x4 r;
;                         if (resb) { const u32x2 w = *(const GASP u32x2*)(resb + (size_t)row * D + c);
;                             r = (f32x4){__uint_as_float(w.x << 16), __uint_as_float(w.x & 0xffff0000u), __uint_as_float(w.y << 16), __uint_as_float(w.y & 0xffff0000u)}; }
;                         else r = *(const GASP f32x4*)(rp + c);
;                         if (STp) r = (r - st[0]) * st[1] * gg[bj][n] + bb[bj][n];
;                         const f32x4 o = r * ALPHA + acc[ai][bj][m][n] * scale;
;                         if (out) *(GASP f32x4*)(op + c) = o;
;                         if (ob) { u32x2 w; w.x = pk2(o[0], o[1]); w.y = pk2(o[2], o[3]); *(GASP u32x2*)(ob + (size_t)row * D + c) = w; }
;                         s += (o[0] + o[1]) + (o[2] + o[3]); q += (o[0] * o[0] + o[1] * o[1]) + (o[2] * o[2] + o[3] * o[3]); }
;                 if (STn) { s += __shfl_xor(s, 16); s += __shfl_xor(s, 32); q += __shfl_xor(q, 16); q += __shfl_xor(q, 32);
;                     if (fq == 0) *(GASP f32x2*)(STn + (size_t)row * 32 + (u.pn * 4 + wc) * 2) = (f32x2){s, q}; }
.LBB0_1044:
	s_or_b64 exec, exec, s[60:61]
	v_add_u32_e32 v176, s37, v180
	v_ashrrev_i32_e32 v64, 31, v176
	v_cmp_gt_i32_e32 vcc, s73, v176
	v_lshl_or_b32 v174, s50, 8, v182
	v_ashrrev_i32_e32 v175, 31, v174
	v_cndmask_b32_e32 v177, 0, v64, vcc
	v_lshlrev_b64 v[64:65], 11, v[176:177]
	v_lshl_add_u64 v[64:65], s[42:43], 0, v[64:65]
	s_waitcnt lgkmcnt(0)
	s_barrier
	v_lshl_add_u64 v[178:179], v[174:175], 1, v[64:65]
	global_load_dwordx2 v[204:205], v[178:179], off
	global_load_dwordx2 v[206:207], v[178:179], off offset:32
	global_load_dwordx2 v[210:211], v[178:179], off offset:256
	v_lshlrev_b64 v[64:65], 2, v[174:175]
	v_lshl_add_u64 v[92:93], s[18:19], 0, v[64:65]
	v_lshl_add_u64 v[88:89], s[16:17], 0, v[64:65]
	global_load_dwordx4 v[64:67], v[92:93], off
	global_load_dwordx4 v[76:79], v[88:89], off
	global_load_dwordx4 v[68:71], v[88:89], off offset:64
	global_load_dwordx4 v[80:83], v[92:93], off offset:64
	global_load_dwordx4 v[72:75], v[88:89], off offset:512
	global_load_dwordx4 v[84:87], v[92:93], off offset:512
	global_load_dwordx2 v[212:213], v[178:179], off offset:288
	ds_read_b64 v[214:215], v184
	global_load_dwordx4 v[88:91], v[88:89], off offset:576
	s_nop 0
	global_load_dwordx4 v[92:95], v[92:93], off offset:576
	s_lshl_b32 s14, s50, 3
	s_or_b32 s14, s14, s69
	s_ashr_i32 s15, s14, 31
	v_add_u32_e32 v242, s37, v185
	v_mov_b32_e32 v243, 0
	v_lshlrev_b64 v[242:243], 11, v[242:243]
	v_lshl_add_u64 v[242:243], s[42:43], 0, v[242:243]
	v_lshl_add_u64 v[242:243], v[174:175], 1, v[242:243]
	global_load_dwordx2 v[236:237], v[242:243], off
	global_load_dwordx2 v[238:239], v[242:243], off offset:32
	global_load_dwordx2 v[240:241], v[242:243], off offset:256
	global_load_dwordx2 v[242:243], v[242:243], off offset:288
	v_add_u32_e32 v250, s37, v187
	v_mov_b32_e32 v251, 0
	v_lshlrev_b64 v[250:251], 11, v[250:251]
	v_lshl_add_u64 v[250:251], s[42:43], 0, v[250:251]
	v_lshl_add_u64 v[250:251], v[174:175], 1, v[250:251]
	global_load_dwordx2 v[244:245], v[250:251], off
	global_load_dwordx2 v[246:247], v[250:251], off offset:32
	global_load_dwordx2 v[248:249], v[250:251], off offset:256
	global_load_dwordx2 v[250:251], v[250:251], off offset:288
	s_waitcnt vmcnt(8)
	v_lshlrev_b32_e32 v165, 16, v204
	v_and_b32_e32 v204, 0xffff0000, v204
	v_lshlrev_b32_e32 v216, 16, v205
	v_and_b32_e32 v217, 0xffff0000, v205
	v_lshlrev_b32_e32 v222, 16, v206
	v_and_b32_e32 v223, 0xffff0000, v206
	v_lshlrev_b32_e32 v224, 16, v207
	v_and_b32_e32 v225, 0xffff0000, v207
	v_lshlrev_b32_e32 v226, 16, v210
	v_and_b32_e32 v227, 0xffff0000, v210
	v_lshlrev_b32_e32 v228, 16, v211
	v_and_b32_e32 v229, 0xffff0000, v211
	s_waitcnt lgkmcnt(0)
	v_sub_f32_e32 v205, v204, v214
	v_sub_f32_e32 v204, v165, v214
	v_sub_f32_e32 v207, v217, v214
	v_sub_f32_e32 v206, v216, v214
	v_sub_f32_e32 v211, v225, v214
	v_sub_f32_e32 v210, v224, v214
	v_sub_f32_e32 v217, v223, v214
	v_sub_f32_e32 v216, v222, v214
	v_pk_mul_f32 v[206:207], v[214:215], v[206:207] op_sel:[1,0]
	v_pk_mul_f32 v[204:205], v[214:215], v[204:205] op_sel:[1,0]
	v_pk_mul_f32 v[216:217], v[214:215], v[216:217] op_sel:[1,0]
	v_pk_mul_f32 v[210:211], v[214:215], v[210:211] op_sel:[1,0]
	v_sub_f32_e32 v219, v229, v214
	v_sub_f32_e32 v218, v228, v214
	v_sub_f32_e32 v221, v227, v214
	v_sub_f32_e32 v220, v226, v214
	v_pk_fma_f32 v[204:205], v[76:77], v[204:205], v[64:65]
	v_pk_fma_f32 v[206:207], v[78:79], v[206:207], v[66:67]
	v_pk_fma_f32 v[210:211], v[70:71], v[210:211], v[82:83]
	v_pk_fma_f32 v[216:217], v[68:69], v[216:217], v[80:81]
	v_pk_mul_f32 v[220:221], v[214:215], v[220:221] op_sel:[1,0]
	v_pk_mul_f32 v[218:219], v[214:215], v[218:219] op_sel:[1,0]
	v_pk_fma_f32 v[158:159], v[206:207], s[34:35], v[158:159] op_sel_hi:[1,0,1]
	v_pk_fma_f32 v[156:157], v[204:205], s[34:35], v[156:157] op_sel_hi:[1,0,1]
	v_cndmask_b32_e64 v205, v217, v223, s[10:11]
	v_cndmask_b32_e64 v204, v216, v222, s[10:11]
	v_cndmask_b32_e64 v207, v211, v225, s[10:11]
	v_cndmask_b32_e64 v206, v210, v224, s[10:11]
	v_pk_fma_f32 v[218:219], v[74:75], v[218:219], v[86:87]
	v_pk_fma_f32 v[220:221], v[72:73], v[220:221], v[84:85]
	v_pk_fma_f32 v[154:155], v[206:207], s[34:35], v[154:155] op_sel_hi:[1,0,1]
	v_pk_fma_f32 v[152:153], v[204:205], s[34:35], v[152:153] op_sel_hi:[1,0,1]
	v_cndmask_b32_e64 v210, v220, v226, s[10:11]
	v_cndmask_b32_e64 v217, v219, v229, s[10:11]
	v_cvt_pk_bf16_f32 v220, v156, v157
	v_add_f32_e32 v222, v156, v157
	v_mul_f32_e32 v219, v156, v156
	v_mul_f32_e32 v157, v157, v157
	v_cvt_pk_bf16_f32 v204, v152, v153
	v_cvt_pk_bf16_f32 v205, v154, v155
	v_mul_f32_e32 v156, v154, v154
	global_store_dwordx2 v[178:179], v[204:205], off offset:32
	v_pk_fma_f32 v[204:205], v[154:155], v[154:155], v[156:157] op_sel_hi:[1,1,0]
	v_cndmask_b32_e64 v211, v221, v227, s[10:11]
	v_lshlrev_b32_e32 v165, 16, v213
	v_and_b32_e32 v204, 0xffff0000, v213
	v_cvt_pk_bf16_f32 v221, v158, v159
	v_add_f32_e32 v224, v158, v159
	v_mul_f32_e32 v227, v158, v158
	v_pk_fma_f32 v[206:207], v[210:211], s[34:35], v[148:149] op_sel_hi:[1,0,1]
	v_lshlrev_b32_e32 v156, 16, v212
	v_and_b32_e32 v158, 0xffff0000, v212
	v_sub_f32_e32 v149, v204, v214
	v_sub_f32_e32 v148, v165, v214
	v_sub_f32_e32 v213, v158, v214
	v_sub_f32_e32 v212, v156, v214
	v_pk_mul_f32 v[148:149], v[214:215], v[148:149] op_sel:[1,0]
	v_pk_mul_f32 v[212:213], v[214:215], v[212:213] op_sel:[1,0]
	v_pk_fma_f32 v[148:149], v[90:91], v[148:149], v[94:95]
	v_pk_fma_f32 v[212:213], v[88:89], v[212:213], v[92:93]
	v_cndmask_b32_e64 v149, v149, v204, s[10:11]
	v_cndmask_b32_e64 v148, v148, v165, s[10:11]
	v_mul_f32_e32 v159, v159, v159
	v_cndmask_b32_e64 v216, v218, v228, s[10:11]
	v_cndmask_b32_e64 v213, v213, v158, s[10:11]
; #define GASP __attribute__((address_space(1)))
;     __device__ __forceinline__ void operator()(Acc& acc, const Unit& u, int wr, int wc, int fr, int fq, LAS unsigned char* lds) const {
;     ...
;                 const int rl = ai * HALF + wr * 64 + m * 16 + fr, row = u.pm * BM + rl;
;                 const float* rp = (row < split) ? res0 + (size_t)row * D : res1 + (size_t)(row - split) * D;
;                 float* op = out + (size_t)row * D;
;                 f32x2 st = (f32x2){0.f, 1.f}; if (STp) st = SL[rl];
;                 float s = 0.f, q = 0.f;
; #pragma unroll
;                 for (int bj = 0; bj < 2; ++bj)
; #pragma unroll
;                     for (int n = 0; n < 2; ++n) { const int c = col0 + bj * HALF + n * 16; f32x4 r;
;                         if (resb) { const u32x2 w = *(const GASP u32x2*)(resb + (size_t)row * D + c);
;                             r = (f32x4){__uint_as_float(w.x << 16), __uint_as_float(w.x & 0xffff0000u), __uint_as_float(w.y << 16), __uint_as_float(w.y & 0xffff0000u)}; }
;                         else r = *(const GASP f32x4*)(rp + c);
;                         if (STp) r = (r - st[0]) * st[1] * gg[bj][n] + bb[bj][n];
;                         const f32x4 o = r * ALPHA + acc[ai][bj][m][n] * scale;
;                         if (out) *(GASP f32x4*)(op + c) = o;
;                         if (ob) { u32x2 w; w.x = pk2(o[0], o[1]); w.y = pk2(o[2], o[3]); *(GASP u32x2*)(ob + (size_t)row * D + c) = w; }
;                         s += (o[0] + o[1]) + (o[2] + o[3]); q += (o[0] * o[0] + o[1] * o[1]) + (o[2] * o[2] + o[3] * o[3]); }
;                 if (STn) { s += __shfl_xor(s, 16); s += __shfl_xor(s, 32); q += __shfl_xor(q, 16); q += __shfl_xor(q, 32);
;                     if (fq == 0) *(GASP f32x2*)(STn + (size_t)row * 32 + (u.pn * 4 + wc) * 2) = (f32x2){s, q}; }
	v_cndmask_b32_e64 v212, v212, v156, s[10:11]
	v_pk_fma_f32 v[214:215], v[148:149], s[34:35], v[146:147] op_sel_hi:[1,0,1]
	v_and_b32_e32 v146, 64, v203
	v_mov_b32_e32 v218, v152
	v_mov_b32_e32 v156, v153
	v_mov_b32_e32 v226, v154
	v_mov_b32_e32 v158, v155
	v_mul_f32_e32 v223, v152, v152
	v_mul_f32_e32 v225, v153, v153
	v_pk_fma_f32 v[212:213], v[212:213], s[34:35], v[144:145] op_sel_hi:[1,0,1]
	v_xor_b32_e32 v144, 16, v203
	v_add_u32_e32 v149, 64, v146
	v_pk_add_f32 v[152:153], v[218:219], v[156:157]
	v_pk_add_f32 v[154:155], v[226:227], v[158:159]
	v_pk_fma_f32 v[150:151], v[216:217], s[34:35], v[150:151] op_sel_hi:[1,0,1]
	v_cmp_lt_i32_e32 vcc, v144, v149
	v_pk_add_f32 v[152:153], v[152:153], v[154:155]
	v_pk_add_f32 v[154:155], v[222:223], v[224:225]
	v_mov_b32_e32 v165, v205
	global_store_dwordx2 v[178:179], v[220:221], off
	v_mul_f32_e32 v217, v206, v206
	v_mul_f32_e32 v221, v207, v207
	v_mul_f32_e32 v229, v150, v150
	v_mul_f32_e32 v231, v151, v151
	v_cndmask_b32_e32 v144, v203, v144, vcc
	v_pk_add_f32 v[154:155], v[154:155], v[164:165]
	v_mov_b32_e32 v216, v206
	v_mov_b32_e32 v220, v207
	v_mov_b32_e32 v228, v150
	v_mov_b32_e32 v230, v151
	v_cvt_pk_bf16_f32 v211, v150, v151
	v_mul_f32_e32 v145, v212, v212
	v_mul_f32_e32 v147, v213, v213
	v_mul_f32_e32 v233, v214, v214
	v_mul_f32_e32 v235, v215, v215
	v_lshlrev_b32_e32 v148, 2, v144
	v_pk_add_f32 v[152:153], v[152:153], v[154:155]
	v_pk_add_f32 v[154:155], v[216:217], v[220:221]
	v_pk_add_f32 v[150:151], v[228:229], v[230:231]
	v_mov_b32_e32 v144, v212
	v_mov_b32_e32 v146, v213
	v_mov_b32_e32 v232, v214
	v_mov_b32_e32 v234, v215
	v_pk_add_f32 v[150:151], v[154:155], v[150:151]
	v_pk_add_f32 v[144:145], v[144:145], v[146:147]
	v_pk_add_f32 v[146:147], v[232:233], v[234:235]
	v_pk_add_f32 v[150:151], v[152:153], v[150:151]
	v_pk_add_f32 v[144:145], v[144:145], v[146:147]
	v_cvt_pk_bf16_f32 v210, v206, v207
	v_pk_add_f32 v[144:145], v[150:151], v[144:145]
	ds_bpermute_b32 v146, v148, v144
	ds_bpermute_b32 v147, v148, v145
	v_xor_b32_e32 v150, 32, v203
	v_cmp_lt_i32_e32 vcc, v150, v149
	v_cvt_pk_bf16_f32 v151, v214, v215
	global_store_dwordx2 v[178:179], v[210:211], off offset:256
	v_cndmask_b32_e32 v149, v203, v150, vcc
	v_lshlrev_b32_e32 v149, 2, v149
	s_waitcnt lgkmcnt(0)
	v_pk_add_f32 v[144:145], v[144:145], v[146:147]
	ds_bpermute_b32 v146, v149, v144
	ds_bpermute_b32 v147, v149, v145
	v_cvt_pk_bf16_f32 v150, v212, v213
	global_store_dwordx2 v[178:179], v[150:151], off offset:288
	s_and_saveexec_b64 s[50:51], s[8:9]
	s_cbranch_execz .LBB0_1046
	s_waitcnt lgkmcnt(0)
	v_pk_add_f32 v[144:145], v[144:145], v[146:147]
	v_lshlrev_b64 v[146:147], 7, v[176:177]
	v_lshl_add_u64 v[146:147], s[24:25], 0, v[146:147]
	v_lshl_add_u64 v[146:147], s[14:15], 2, v[146:147]
	global_store_dwordx2 v[146:147], v[144:145], off
.LBB0_1046:
	s_or_b64 exec, exec, s[50:51]
	v_add_u32_e32 v144, s37, v185
	v_ashrrev_i32_e32 v145, 31, v144
	v_cmp_gt_i32_e32 vcc, s73, v144
	s_nop 1
	v_cndmask_b32_e32 v145, 0, v145, vcc
	s_waitcnt lgkmcnt(0)
	v_lshlrev_b64 v[146:147], 11, v[144:145]
	v_lshl_add_u64 v[146:147], s[42:43], 0, v[146:147]
	v_lshl_add_u64 v[146:147], v[174:175], 1, v[146:147]
	ds_read_b64 v[158:159], v186
	s_waitcnt vmcnt(9)
	v_lshlrev_b32_e32 v176, 16, v237
	v_and_b32_e32 v177, 0xffff0000, v237
	v_lshlrev_b32_e32 v212, 16, v239
	v_and_b32_e32 v213, 0xffff0000, v239
	v_lshlrev_b32_e32 v165, 16, v236
	v_and_b32_e32 v150, 0xffff0000, v236
	v_lshlrev_b32_e32 v210, 16, v238
	v_and_b32_e32 v211, 0xffff0000, v238
	v_lshlrev_b32_e32 v214, 16, v240
	v_and_b32_e32 v215, 0xffff0000, v240
	v_lshlrev_b32_e32 v216, 16, v241
	v_and_b32_e32 v217, 0xffff0000, v241
	s_waitcnt lgkmcnt(0)
	v_sub_f32_e32 v153, v177, v158
	v_sub_f32_e32 v152, v176, v158
	v_sub_f32_e32 v155, v213, v158
	v_sub_f32_e32 v154, v212, v158
	v_lshlrev_b32_e32 v218, 16, v242
	v_and_b32_e32 v219, 0xffff0000, v242
	v_lshlrev_b32_e32 v220, 16, v243
	v_and_b32_e32 v221, 0xffff0000, v243
	v_add_u32_e32 v242, s37, v189
	v_mov_b32_e32 v243, 0
	v_lshlrev_b64 v[242:243], 11, v[242:243]
	v_lshl_add_u64 v[242:243], s[42:43], 0, v[242:243]
	v_lshl_add_u64 v[242:243], v[174:175], 1, v[242:243]
	global_load_dwordx2 v[236:237], v[242:243], off
	global_load_dwordx2 v[238:239], v[242:243], off offset:32
	global_load_dwordx2 v[240:241], v[242:243], off offset:256
	global_load_dwordx2 v[242:243], v[242:243], off offset:288
	v_sub_f32_e32 v151, v150, v158
	v_sub_f32_e32 v150, v165, v158
	v_sub_f32_e32 v157, v211, v158
	v_sub_f32_e32 v156, v210, v158
	v_pk_mul_f32 v[152:153], v[158:159], v[152:153] op_sel:[1,0]
	v_pk_mul_f32 v[154:155], v[158:159], v[154:155] op_sel:[1,0]
	v_sub_f32_e32 v177, v217, v158
	v_sub_f32_e32 v176, v216, v158
	v_sub_f32_e32 v179, v215, v158
	v_sub_f32_e32 v178, v214, v158
	v_sub_f32_e32 v207, v219, v158
	v_sub_f32_e32 v206, v218, v158
	v_pk_mul_f32 v[150:151], v[158:159], v[150:151] op_sel:[1,0]
	v_pk_mul_f32 v[156:157], v[158:159], v[156:157] op_sel:[1,0]
	v_pk_fma_f32 v[152:153], v[78:79], v[152:153], v[66:67]
	v_pk_fma_f32 v[154:155], v[70:71], v[154:155], v[82:83]
	v_sub_f32_e32 v205, v221, v158
	v_sub_f32_e32 v204, v220, v158
	v_pk_mul_f32 v[178:179], v[158:159], v[178:179] op_sel:[1,0]
	v_pk_mul_f32 v[176:177], v[158:159], v[176:177] op_sel:[1,0]
	v_pk_mul_f32 v[206:207], v[158:159], v[206:207] op_sel:[1,0]
	v_pk_fma_f32 v[150:151], v[76:77], v[150:151], v[64:65]
	v_pk_fma_f32 v[156:157], v[68:69], v[156:157], v[80:81]
	v_pk_fma_f32 v[142:143], v[152:153], s[34:35], v[142:143] op_sel_hi:[1,0,1]
	v_cndmask_b32_e64 v153, v155, v213, s[10:11]
	v_cndmask_b32_e64 v152, v154, v212, s[10:11]
	v_pk_mul_f32 v[158:159], v[158:159], v[204:205] op_sel:[1,0]
; #define GASP __attribute__((address_space(1)))
;     __device__ __forceinline__ void operator()(Acc& acc, const Unit& u, int wr, int wc, int fr, int fq, LAS unsigned char* lds) const {
;     ...
;                 const int rl = ai * HALF + wr * 64 + m * 16 + fr, row = u.pm * BM + rl;
;                 const float* rp = (row < split) ? res0 + (size_t)row * D : res1 + (size_t)(row - split) * D;
;                 float* op = out + (size_t)row * D;
;                 f32x2 st = (f32x2){0.f, 1.f}; if (STp) st = SL[rl];
;                 float s = 0.f, q = 0.f;
; #pragma unroll
;                 for (int bj = 0; bj < 2; ++bj)
; #pragma unroll
;                     for (int n = 0; n < 2; ++n) { const int c = col0 + bj * HALF + n * 16; f32x4 r;
;                         if (resb) { const u32x2 w = *(const GASP u32x2*)(resb + (size_t)row * D + c);
;                             r = (f32x4){__uint_as_float(w.x << 16), __uint_as_float(w.x & 0xffff0000u), __uint_as_float(w.y << 16), __uint_as_float(w.y & 0xffff0000u)}; }
;                         else r = *(const GASP f32x4*)(rp + c);
;                         if (STp) r = (r - st[0]) * st[1] * gg[bj][n] + bb[bj][n];
;                         const f32x4 o = r * ALPHA + acc[ai][bj][m][n] * scale;
;                         if (out) *(GASP f32x4*)(op + c) = o;
;                         if (ob) { u32x2 w; w.x = pk2(o[0], o[1]); w.y = pk2(o[2], o[3]); *(GASP u32x2*)(ob + (size_t)row * D + c) = w; }
;                         s += (o[0] + o[1]) + (o[2] + o[3]); q += (o[0] * o[0] + o[1] * o[1]) + (o[2] * o[2] + o[3] * o[3]); }
;                 if (STn) { s += __shfl_xor(s, 16); s += __shfl_xor(s, 32); q += __shfl_xor(q, 16); q += __shfl_xor(q, 32);
;                     if (fq == 0) *(GASP f32x2*)(STn + (size_t)row * 32 + (u.pn * 4 + wc) * 2) = (f32x2){s, q}; }
	v_pk_fma_f32 v[176:177], v[74:75], v[176:177], v[86:87]
	v_pk_fma_f32 v[178:179], v[72:73], v[178:179], v[84:85]
	v_pk_fma_f32 v[204:205], v[88:89], v[206:207], v[92:93]
	v_pk_fma_f32 v[140:141], v[150:151], s[34:35], v[140:141] op_sel_hi:[1,0,1]
	v_cndmask_b32_e64 v151, v157, v211, s[10:11]
	v_cndmask_b32_e64 v150, v156, v210, s[10:11]
	v_pk_fma_f32 v[138:139], v[152:153], s[34:35], v[138:139] op_sel_hi:[1,0,1]
	v_cndmask_b32_e64 v154, v178, v214, s[10:11]
	v_cndmask_b32_e64 v156, v176, v216, s[10:11]
	v_cndmask_b32_e64 v176, v204, v218, s[10:11]
	v_cvt_pk_bf16_f32 v178, v140, v141
	v_add_f32_e32 v204, v140, v141
	v_mul_f32_e32 v211, v140, v140
	v_mul_f32_e32 v141, v141, v141
	v_pk_fma_f32 v[136:137], v[150:151], s[34:35], v[136:137] op_sel_hi:[1,0,1]
	v_mul_f32_e32 v140, v138, v138
	v_cndmask_b32_e64 v155, v179, v215, s[10:11]
	v_cvt_pk_bf16_f32 v179, v142, v143
	v_add_f32_e32 v206, v142, v143
	v_mul_f32_e32 v213, v142, v142
	v_mul_f32_e32 v143, v143, v143
	v_pk_fma_f32 v[214:215], v[138:139], v[138:139], v[140:141] op_sel_hi:[1,1,0]
	v_mov_b32_e32 v210, v136
	v_mov_b32_e32 v140, v137
	v_mov_b32_e32 v212, v138
	v_mov_b32_e32 v142, v139
	v_pk_fma_f32 v[158:159], v[90:91], v[158:159], v[94:95]
	v_cndmask_b32_e64 v157, v177, v217, s[10:11]
	v_cndmask_b32_e64 v177, v205, v219, s[10:11]
	v_cvt_pk_bf16_f32 v150, v136, v137
	v_mul_f32_e32 v205, v136, v136
	v_mul_f32_e32 v207, v137, v137
	v_pk_add_f32 v[136:137], v[210:211], v[140:141]
	v_pk_add_f32 v[140:141], v[212:213], v[142:143]
	v_pk_fma_f32 v[134:135], v[156:157], s[34:35], v[134:135] op_sel_hi:[1,0,1]
	v_pk_fma_f32 v[132:133], v[154:155], s[34:35], v[132:133] op_sel_hi:[1,0,1]
	v_cndmask_b32_e64 v159, v159, v221, s[10:11]
	v_cndmask_b32_e64 v158, v158, v220, s[10:11]
	v_pk_add_f32 v[136:137], v[136:137], v[140:141]
	v_pk_add_f32 v[140:141], v[204:205], v[206:207]
	v_mov_b32_e32 v165, v215
	global_store_dwordx2 v[146:147], v[178:179], off
	v_mul_f32_e32 v153, v132, v132
	v_mul_f32_e32 v155, v133, v133
	v_mul_f32_e32 v157, v134, v134
	v_mul_f32_e32 v179, v135, v135
	v_pk_fma_f32 v[158:159], v[158:159], s[34:35], v[130:131] op_sel_hi:[1,0,1]
	v_pk_fma_f32 v[176:177], v[176:177], s[34:35], v[128:129] op_sel_hi:[1,0,1]
	v_pk_add_f32 v[140:141], v[140:141], v[164:165]
	v_mov_b32_e32 v152, v132
	v_mov_b32_e32 v154, v133
	v_mov_b32_e32 v156, v134
	v_mov_b32_e32 v178, v135
	v_mul_f32_e32 v129, v176, v176
	v_mul_f32_e32 v131, v177, v177
	v_mul_f32_e32 v217, v158, v158
	v_mul_f32_e32 v219, v159, v159
	v_pk_add_f32 v[136:137], v[136:137], v[140:141]
	v_pk_add_f32 v[140:141], v[152:153], v[154:155]
	v_pk_add_f32 v[142:143], v[156:157], v[178:179]
	v_mov_b32_e32 v128, v176
	v_mov_b32_e32 v130, v177
	v_mov_b32_e32 v216, v158
	v_mov_b32_e32 v218, v159
	v_pk_add_f32 v[140:141], v[140:141], v[142:143]
	v_pk_add_f32 v[128:129], v[128:129], v[130:131]
	v_pk_add_f32 v[130:131], v[216:217], v[218:219]
	v_pk_add_f32 v[136:137], v[136:137], v[140:141]
	v_pk_add_f32 v[128:129], v[128:129], v[130:131]
	v_cvt_pk_bf16_f32 v132, v132, v133
	v_pk_add_f32 v[128:129], v[136:137], v[128:129]
	ds_bpermute_b32 v130, v148, v128
	ds_bpermute_b32 v131, v148, v129
	v_cvt_pk_bf16_f32 v133, v134, v135
	v_cvt_pk_bf16_f32 v151, v138, v139
	global_store_dwordx2 v[146:147], v[132:133], off offset:256
	v_cvt_pk_bf16_f32 v132, v176, v177
	s_waitcnt lgkmcnt(0)
	v_pk_add_f32 v[128:129], v[128:129], v[130:131]
	ds_bpermute_b32 v130, v149, v128
	ds_bpermute_b32 v131, v149, v129
	v_cvt_pk_bf16_f32 v133, v158, v159
	global_store_dwordx2 v[146:147], v[150:151], off offset:32
	global_store_dwordx2 v[146:147], v[132:133], off offset:288
	s_and_saveexec_b64 s[50:51], s[8:9]
	s_cbranch_execz .LBB0_1048
	s_waitcnt lgkmcnt(0)
	v_pk_add_f32 v[128:129], v[128:129], v[130:131]
	v_lshlrev_b64 v[130:131], 7, v[144:145]
	v_lshl_add_u64 v[130:131], s[24:25], 0, v[130:131]
	v_lshl_add_u64 v[130:131], s[14:15], 2, v[130:131]
	global_store_dwordx2 v[130:131], v[128:129], off
.LBB0_1048:
	s_or_b64 exec, exec, s[50:51]
	v_add_u32_e32 v128, s37, v187
	v_ashrrev_i32_e32 v129, 31, v128
	v_cmp_gt_i32_e32 vcc, s73, v128
	s_nop 1
	v_cndmask_b32_e32 v129, 0, v129, vcc
	s_waitcnt lgkmcnt(0)
	v_lshlrev_b64 v[130:131], 11, v[128:129]
	v_lshl_add_u64 v[130:131], s[42:43], 0, v[130:131]
	v_lshl_add_u64 v[130:131], v[174:175], 1, v[130:131]
	ds_read_b64 v[140:141], v188
	s_waitcnt vmcnt(14)
	v_lshlrev_b32_e32 v143, 16, v245
	v_and_b32_e32 v144, 0xffff0000, v245
	v_lshlrev_b32_e32 v154, 16, v247
	v_and_b32_e32 v155, 0xffff0000, v247
	v_lshlrev_b32_e32 v142, 16, v244
	v_and_b32_e32 v132, 0xffff0000, v244
	v_lshlrev_b32_e32 v152, 16, v246
	v_and_b32_e32 v153, 0xffff0000, v246
	v_lshlrev_b32_e32 v156, 16, v248
	v_and_b32_e32 v157, 0xffff0000, v248
	v_lshlrev_b32_e32 v158, 16, v249
	v_and_b32_e32 v159, 0xffff0000, v249
	s_waitcnt lgkmcnt(0)
; #define GASP __attribute__((address_space(1)))
;     __device__ __forceinline__ void operator()(Acc& acc, const Unit& u, int wr, int wc, int fr, int fq, LAS unsigned char* lds) const {
;     ...
;                 const int rl = ai * HALF + wr * 64 + m * 16 + fr, row = u.pm * BM + rl;
;                 const float* rp = (row < split) ? res0 + (size_t)row * D : res1 + (size_t)(row - split) * D;
;                 float* op = out + (size_t)row * D;
;                 f32x2 st = (f32x2){0.f, 1.f}; if (STp) st = SL[rl];
;                 float s = 0.f, q = 0.f;
; #pragma unroll
;                 for (int bj = 0; bj < 2; ++bj)
; #pragma unroll
;                     for (int n = 0; n < 2; ++n) { const int c = col0 + bj * HALF + n * 16; f32x4 r;
;                         if (resb) { const u32x2 w = *(const GASP u32x2*)(resb + (size_t)row * D + c);
;                             r = (f32x4){__uint_as_float(w.x << 16), __uint_as_float(w.x & 0xffff0000u), __uint_as_float(w.y << 16), __uint_as_float(w.y & 0xffff0000u)}; }
;                         else r = *(const GASP f32x4*)(rp + c);
;                         if (STp) r = (r - st[0]) * st[1] * gg[bj][n] + bb[bj][n];
;                         const f32x4 o = r * ALPHA + acc[ai][bj][m][n] * scale;
;                         if (out) *(GASP f32x4*)(op + c) = o;
;                         if (ob) { u32x2 w; w.x = pk2(o[0], o[1]); w.y = pk2(o[2], o[3]); *(GASP u32x2*)(ob + (size_t)row * D + c) = w; }
;                         s += (o[0] + o[1]) + (o[2] + o[3]); q += (o[0] * o[0] + o[1] * o[1]) + (o[2] * o[2] + o[3] * o[3]); }
;                 if (STn) { s += __shfl_xor(s, 16); s += __shfl_xor(s, 32); q += __shfl_xor(q, 16); q += __shfl_xor(q, 32);
;                     if (fq == 0) *(GASP f32x2*)(STn + (size_t)row * 32 + (u.pn * 4 + wc) * 2) = (f32x2){s, q}; }
	v_sub_f32_e32 v135, v144, v140
	v_sub_f32_e32 v134, v143, v140
	v_sub_f32_e32 v137, v155, v140
	v_sub_f32_e32 v136, v154, v140
	v_lshlrev_b32_e32 v165, 16, v250
	v_and_b32_e32 v176, 0xffff0000, v250
	v_lshlrev_b32_e32 v177, 16, v251
	v_and_b32_e32 v178, 0xffff0000, v251
	v_add_u32_e32 v250, s37, v191
	v_mov_b32_e32 v251, 0
	v_lshlrev_b64 v[250:251], 11, v[250:251]
	v_lshl_add_u64 v[250:251], s[42:43], 0, v[250:251]
	v_lshl_add_u64 v[250:251], v[174:175], 1, v[250:251]
	global_load_dwordx2 v[244:245], v[250:251], off
	global_load_dwordx2 v[246:247], v[250:251], off offset:32
	global_load_dwordx2 v[248:249], v[250:251], off offset:256
	global_load_dwordx2 v[250:251], v[250:251], off offset:288
	v_sub_f32_e32 v133, v132, v140
	v_sub_f32_e32 v132, v142, v140
	v_sub_f32_e32 v139, v153, v140
	v_sub_f32_e32 v138, v152, v140
	v_pk_mul_f32 v[134:135], v[140:141], v[134:135] op_sel:[1,0]
	v_pk_mul_f32 v[136:137], v[140:141], v[136:137] op_sel:[1,0]
	v_sub_f32_e32 v143, v159, v140
	v_sub_f32_e32 v142, v158, v140
	v_sub_f32_e32 v145, v157, v140
	v_sub_f32_e32 v144, v156, v140
	v_sub_f32_e32 v151, v176, v140
	v_sub_f32_e32 v150, v165, v140
	v_pk_mul_f32 v[132:133], v[140:141], v[132:133] op_sel:[1,0]
	v_pk_mul_f32 v[138:139], v[140:141], v[138:139] op_sel:[1,0]
	v_pk_fma_f32 v[134:135], v[78:79], v[134:135], v[66:67]
	v_pk_fma_f32 v[136:137], v[70:71], v[136:137], v[82:83]
	v_sub_f32_e32 v147, v178, v140
	v_sub_f32_e32 v146, v177, v140
	v_pk_mul_f32 v[144:145], v[140:141], v[144:145] op_sel:[1,0]
	v_pk_mul_f32 v[142:143], v[140:141], v[142:143] op_sel:[1,0]
	v_pk_mul_f32 v[150:151], v[140:141], v[150:151] op_sel:[1,0]
	v_pk_fma_f32 v[132:133], v[76:77], v[132:133], v[64:65]
	v_pk_fma_f32 v[138:139], v[68:69], v[138:139], v[80:81]
	v_pk_fma_f32 v[126:127], v[134:135], s[34:35], v[126:127] op_sel_hi:[1,0,1]
	v_cndmask_b32_e64 v135, v137, v155, s[10:11]
	v_cndmask_b32_e64 v134, v136, v154, s[10:11]
	v_pk_mul_f32 v[140:141], v[140:141], v[146:147] op_sel:[1,0]
	v_pk_fma_f32 v[142:143], v[74:75], v[142:143], v[86:87]
	v_pk_fma_f32 v[144:145], v[72:73], v[144:145], v[84:85]
	v_pk_fma_f32 v[146:147], v[88:89], v[150:151], v[92:93]
	v_pk_fma_f32 v[124:125], v[132:133], s[34:35], v[124:125] op_sel_hi:[1,0,1]
	v_cndmask_b32_e64 v133, v139, v153, s[10:11]
	v_cndmask_b32_e64 v132, v138, v152, s[10:11]
	v_pk_fma_f32 v[122:123], v[134:135], s[34:35], v[122:123] op_sel_hi:[1,0,1]
	v_cndmask_b32_e64 v136, v144, v156, s[10:11]
	v_cndmask_b32_e64 v138, v142, v158, s[10:11]
	v_cndmask_b32_e64 v142, v146, v165, s[10:11]
	v_cvt_pk_bf16_f32 v144, v124, v125
	v_add_f32_e32 v146, v124, v125
	v_mul_f32_e32 v153, v124, v124
	v_mul_f32_e32 v125, v125, v125
	v_pk_fma_f32 v[120:121], v[132:133], s[34:35], v[120:121] op_sel_hi:[1,0,1]
	v_mul_f32_e32 v124, v122, v122
	v_cndmask_b32_e64 v137, v145, v157, s[10:11]
	v_cvt_pk_bf16_f32 v145, v126, v127
	v_add_f32_e32 v150, v126, v127
	v_mul_f32_e32 v155, v126, v126
	v_mul_f32_e32 v127, v127, v127
	v_pk_fma_f32 v[156:157], v[122:123], v[122:123], v[124:125] op_sel_hi:[1,1,0]
	v_mov_b32_e32 v152, v120
	v_mov_b32_e32 v124, v121
	v_mov_b32_e32 v154, v122
	v_mov_b32_e32 v126, v123
	v_pk_fma_f32 v[140:141], v[90:91], v[140:141], v[94:95]
	v_cndmask_b32_e64 v139, v143, v159, s[10:11]
	v_cndmask_b32_e64 v143, v147, v176, s[10:11]
	v_cvt_pk_bf16_f32 v132, v120, v121
	v_mul_f32_e32 v147, v120, v120
	v_mul_f32_e32 v151, v121, v121
	v_pk_add_f32 v[120:121], v[152:153], v[124:125]
	v_pk_add_f32 v[124:125], v[154:155], v[126:127]
	v_pk_fma_f32 v[118:119], v[138:139], s[34:35], v[118:119] op_sel_hi:[1,0,1]
	v_pk_fma_f32 v[116:117], v[136:137], s[34:35], v[116:117] op_sel_hi:[1,0,1]
	v_cndmask_b32_e64 v141, v141, v178, s[10:11]
	v_cndmask_b32_e64 v140, v140, v177, s[10:11]
	v_pk_add_f32 v[120:121], v[120:121], v[124:125]
	v_pk_add_f32 v[124:125], v[146:147], v[150:151]
	v_mov_b32_e32 v165, v157
	global_store_dwordx2 v[130:131], v[144:145], off
	v_mul_f32_e32 v135, v116, v116
	v_mul_f32_e32 v137, v117, v117
	v_mul_f32_e32 v139, v118, v118
	v_mul_f32_e32 v145, v119, v119
	v_pk_fma_f32 v[140:141], v[140:141], s[34:35], v[114:115] op_sel_hi:[1,0,1]
	v_pk_fma_f32 v[142:143], v[142:143], s[34:35], v[112:113] op_sel_hi:[1,0,1]
	v_pk_add_f32 v[124:125], v[124:125], v[164:165]
	v_mov_b32_e32 v134, v116
	v_mov_b32_e32 v136, v117
	v_mov_b32_e32 v138, v118
	v_mov_b32_e32 v144, v119
	v_mul_f32_e32 v113, v142, v142
	v_mul_f32_e32 v115, v143, v143
	v_mul_f32_e32 v159, v140, v140
	v_mul_f32_e32 v177, v141, v141
	v_pk_add_f32 v[120:121], v[120:121], v[124:125]
	v_pk_add_f32 v[124:125], v[134:135], v[136:137]
	v_pk_add_f32 v[126:127], v[138:139], v[144:145]
	v_mov_b32_e32 v112, v142
	v_mov_b32_e32 v114, v143
	v_mov_b32_e32 v158, v140
	v_mov_b32_e32 v176, v141
	v_pk_add_f32 v[124:125], v[124:125], v[126:127]
	v_pk_add_f32 v[112:113], v[112:113], v[114:115]
	v_pk_add_f32 v[114:115], v[158:159], v[176:177]
	v_pk_add_f32 v[120:121], v[120:121], v[124:125]
	v_pk_add_f32 v[112:113], v[112:113], v[114:115]
	v_cvt_pk_bf16_f32 v116, v116, v117
	v_pk_add_f32 v[112:113], v[120:121], v[112:113]
	ds_bpermute_b32 v114, v148, v112
	ds_bpermute_b32 v115, v148, v113
	v_cvt_pk_bf16_f32 v117, v118, v119
	v_cvt_pk_bf16_f32 v133, v122, v123
	global_store_dwordx2 v[130:131], v[116:117], off offset:256
	v_cvt_pk_bf16_f32 v116, v142, v143
	s_waitcnt lgkmcnt(0)
	v_pk_add_f32 v[112:113], v[112:113], v[114:115]
	ds_bpermute_b32 v114, v149, v112
	ds_bpermute_b32 v115, v149, v113
	v_cvt_pk_bf16_f32 v117, v140, v141
	global_store_dwordx2 v[130:131], v[132:133], off offset:32
	global_store_dwordx2 v[130:131], v[116:117], off offset:288
	s_and_saveexec_b64 s[50:51], s[8:9]
	s_cbranch_execz .LBB0_1050
	s_waitcnt lgkmcnt(0)
	v_pk_add_f32 v[112:113], v[112:113], v[114:115]
	v_lshlrev_b64 v[114:115], 7, v[128:129]
	v_lshl_add_u64 v[114:115], s[24:25], 0, v[114:115]
	v_lshl_add_u64 v[114:115], s[14:15], 2, v[114:115]
	global_store_dwordx2 v[114:115], v[112:113], off
; #define GASP __attribute__((address_space(1)))
;     __device__ __forceinline__ void operator()(Acc& acc, const Unit& u, int wr, int wc, int fr, int fq, LAS unsigned char* lds) const {
;     ...
;                 const int rl = ai * HALF + wr * 64 + m * 16 + fr, row = u.pm * BM + rl;
;                 const float* rp = (row < split) ? res0 + (size_t)row * D : res1 + (size_t)(row - split) * D;
;                 float* op = out + (size_t)row * D;
;                 f32x2 st = (f32x2){0.f, 1.f}; if (STp) st = SL[rl];
;                 float s = 0.f, q = 0.f;
; #pragma unroll
;                 for (int bj = 0; bj < 2; ++bj)
; #pragma unroll
;                     for (int n = 0; n < 2; ++n) { const int c = col0 + bj * HALF + n * 16; f32x4 r;
;                         if (resb) { const u32x2 w = *(const GASP u32x2*)(resb + (size_t)row * D + c);
;                             r = (f32x4){__uint_as_float(w.x << 16), __uint_as_float(w.x & 0xffff0000u), __uint_as_float(w.y << 16), __uint_as_float(w.y & 0xffff0000u)}; }
;                         else r = *(const GASP f32x4*)(rp + c);
;                         if (STp) r = (r - st[0]) * st[1] * gg[bj][n] + bb[bj][n];
;                         const f32x4 o = r * ALPHA + acc[ai][bj][m][n] * scale;
;                         if (out) *(GASP f32x4*)(op + c) = o;
;                         if (ob) { u32x2 w; w.x = pk2(o[0], o[1]); w.y = pk2(o[2], o[3]); *(GASP u32x2*)(ob + (size_t)row * D + c) = w; }
;                         s += (o[0] + o[1]) + (o[2] + o[3]); q += (o[0] * o[0] + o[1] * o[1]) + (o[2] * o[2] + o[3] * o[3]); }
;                 if (STn) { s += __shfl_xor(s, 16); s += __shfl_xor(s, 32); q += __shfl_xor(q, 16); q += __shfl_xor(q, 32);
;                     if (fq == 0) *(GASP f32x2*)(STn + (size_t)row * 32 + (u.pn * 4 + wc) * 2) = (f32x2){s, q}; }
.LBB0_1050:
	s_or_b64 exec, exec, s[50:51]
	v_add_u32_e32 v112, s37, v189
	v_ashrrev_i32_e32 v113, 31, v112
	v_cmp_gt_i32_e32 vcc, s73, v112
	s_nop 1
	v_cndmask_b32_e32 v113, 0, v113, vcc
	s_waitcnt lgkmcnt(0)
	v_lshlrev_b64 v[114:115], 11, v[112:113]
	v_lshl_add_u64 v[114:115], s[42:43], 0, v[114:115]
	v_lshl_add_u64 v[114:115], v[174:175], 1, v[114:115]
	ds_read_b64 v[124:125], v190
	s_waitcnt vmcnt(14)
	v_lshlrev_b32_e32 v127, 16, v237
	v_and_b32_e32 v128, 0xffff0000, v237
	v_lshlrev_b32_e32 v136, 16, v239
	v_and_b32_e32 v137, 0xffff0000, v239
	v_lshlrev_b32_e32 v126, 16, v236
	v_and_b32_e32 v116, 0xffff0000, v236
	v_lshlrev_b32_e32 v134, 16, v238
	v_and_b32_e32 v135, 0xffff0000, v238
	v_lshlrev_b32_e32 v138, 16, v240
	v_and_b32_e32 v139, 0xffff0000, v240
	v_lshlrev_b32_e32 v140, 16, v241
	v_and_b32_e32 v141, 0xffff0000, v241
	s_waitcnt lgkmcnt(0)
	v_sub_f32_e32 v119, v128, v124
	v_sub_f32_e32 v118, v127, v124
	v_sub_f32_e32 v121, v137, v124
	v_sub_f32_e32 v120, v136, v124
	v_lshlrev_b32_e32 v142, 16, v242
	v_and_b32_e32 v143, 0xffff0000, v242
	v_lshlrev_b32_e32 v144, 16, v243
	v_and_b32_e32 v145, 0xffff0000, v243
	v_add_u32_e32 v242, s37, v193
	v_mov_b32_e32 v243, 0
	v_lshlrev_b64 v[242:243], 11, v[242:243]
	v_lshl_add_u64 v[242:243], s[42:43], 0, v[242:243]
	v_lshl_add_u64 v[242:243], v[174:175], 1, v[242:243]
	global_load_dwordx2 v[236:237], v[242:243], off
	global_load_dwordx2 v[238:239], v[242:243], off offset:32
	global_load_dwordx2 v[240:241], v[242:243], off offset:256
	global_load_dwordx2 v[242:243], v[242:243], off offset:288
	v_sub_f32_e32 v117, v116, v124
	v_sub_f32_e32 v116, v126, v124
	v_sub_f32_e32 v123, v135, v124
	v_sub_f32_e32 v122, v134, v124
	v_pk_mul_f32 v[118:119], v[124:125], v[118:119] op_sel:[1,0]
	v_pk_mul_f32 v[120:121], v[124:125], v[120:121] op_sel:[1,0]
	v_sub_f32_e32 v127, v141, v124
	v_sub_f32_e32 v126, v140, v124
	v_sub_f32_e32 v129, v139, v124
	v_sub_f32_e32 v128, v138, v124
	v_sub_f32_e32 v133, v143, v124
	v_sub_f32_e32 v132, v142, v124
	v_pk_mul_f32 v[116:117], v[124:125], v[116:117] op_sel:[1,0]
	v_pk_mul_f32 v[122:123], v[124:125], v[122:123] op_sel:[1,0]
	v_pk_fma_f32 v[118:119], v[78:79], v[118:119], v[66:67]
	v_pk_fma_f32 v[120:121], v[70:71], v[120:121], v[82:83]
	v_sub_f32_e32 v131, v145, v124
	v_sub_f32_e32 v130, v144, v124
	v_pk_mul_f32 v[128:129], v[124:125], v[128:129] op_sel:[1,0]
	v_pk_mul_f32 v[126:127], v[124:125], v[126:127] op_sel:[1,0]
	v_pk_mul_f32 v[132:133], v[124:125], v[132:133] op_sel:[1,0]
	v_pk_fma_f32 v[116:117], v[76:77], v[116:117], v[64:65]
	v_pk_fma_f32 v[122:123], v[68:69], v[122:123], v[80:81]
	v_pk_fma_f32 v[110:111], v[118:119], s[34:35], v[110:111] op_sel_hi:[1,0,1]
	v_cndmask_b32_e64 v119, v121, v137, s[10:11]
	v_cndmask_b32_e64 v118, v120, v136, s[10:11]
	v_pk_mul_f32 v[124:125], v[124:125], v[130:131] op_sel:[1,0]
	v_pk_fma_f32 v[126:127], v[74:75], v[126:127], v[86:87]
	v_pk_fma_f32 v[128:129], v[72:73], v[128:129], v[84:85]
	v_pk_fma_f32 v[130:131], v[88:89], v[132:133], v[92:93]
	v_pk_fma_f32 v[108:109], v[116:117], s[34:35], v[108:109] op_sel_hi:[1,0,1]
	v_cndmask_b32_e64 v117, v123, v135, s[10:11]
	v_cndmask_b32_e64 v116, v122, v134, s[10:11]
	v_pk_fma_f32 v[106:107], v[118:119], s[34:35], v[106:107] op_sel_hi:[1,0,1]
	v_cndmask_b32_e64 v120, v128, v138, s[10:11]
	v_cndmask_b32_e64 v122, v126, v140, s[10:11]
	v_cndmask_b32_e64 v126, v130, v142, s[10:11]
	v_cvt_pk_bf16_f32 v128, v108, v109
	v_add_f32_e32 v130, v108, v109
	v_mul_f32_e32 v135, v108, v108
	v_mul_f32_e32 v109, v109, v109
	v_pk_fma_f32 v[104:105], v[116:117], s[34:35], v[104:105] op_sel_hi:[1,0,1]
	v_mul_f32_e32 v108, v106, v106
	v_cndmask_b32_e64 v121, v129, v139, s[10:11]
	v_cvt_pk_bf16_f32 v129, v110, v111
	v_add_f32_e32 v132, v110, v111
	v_mul_f32_e32 v137, v110, v110
	v_mul_f32_e32 v111, v111, v111
	v_pk_fma_f32 v[138:139], v[106:107], v[106:107], v[108:109] op_sel_hi:[1,1,0]
	v_mov_b32_e32 v134, v104
	v_mov_b32_e32 v108, v105
	v_mov_b32_e32 v136, v106
	v_mov_b32_e32 v110, v107
	v_pk_fma_f32 v[124:125], v[90:91], v[124:125], v[94:95]
	v_cndmask_b32_e64 v123, v127, v141, s[10:11]
	v_cndmask_b32_e64 v127, v131, v143, s[10:11]
	v_cvt_pk_bf16_f32 v116, v104, v105
	v_mul_f32_e32 v131, v104, v104
	v_mul_f32_e32 v133, v105, v105
	v_pk_add_f32 v[104:105], v[134:135], v[108:109]
	v_pk_add_f32 v[108:109], v[136:137], v[110:111]
	v_pk_fma_f32 v[102:103], v[122:123], s[34:35], v[102:103] op_sel_hi:[1,0,1]
	v_pk_fma_f32 v[100:101], v[120:121], s[34:35], v[100:101] op_sel_hi:[1,0,1]
	v_cndmask_b32_e64 v125, v125, v145, s[10:11]
	v_cndmask_b32_e64 v124, v124, v144, s[10:11]
	v_pk_add_f32 v[104:105], v[104:105], v[108:109]
	v_pk_add_f32 v[108:109], v[130:131], v[132:133]
	v_mov_b32_e32 v165, v139
	global_store_dwordx2 v[114:115], v[128:129], off
	v_mul_f32_e32 v119, v100, v100
	v_mul_f32_e32 v121, v101, v101
	v_mul_f32_e32 v123, v102, v102
	v_mul_f32_e32 v129, v103, v103
	v_pk_fma_f32 v[124:125], v[124:125], s[34:35], v[98:99] op_sel_hi:[1,0,1]
	v_pk_fma_f32 v[126:127], v[126:127], s[34:35], v[96:97] op_sel_hi:[1,0,1]
	v_pk_add_f32 v[108:109], v[108:109], v[164:165]
	v_mov_b32_e32 v118, v100
	v_mov_b32_e32 v120, v101
	v_mov_b32_e32 v122, v102
	v_mov_b32_e32 v128, v103
	v_mul_f32_e32 v97, v126, v126
	v_mul_f32_e32 v99, v127, v127
	v_mul_f32_e32 v141, v124, v124
	v_mul_f32_e32 v143, v125, v125
	v_pk_add_f32 v[104:105], v[104:105], v[108:109]
	v_pk_add_f32 v[108:109], v[118:119], v[120:121]
	v_pk_add_f32 v[110:111], v[122:123], v[128:129]
	v_mov_b32_e32 v96, v126
	v_mov_b32_e32 v98, v127
	v_mov_b32_e32 v140, v124
	v_mov_b32_e32 v142, v125
	v_pk_add_f32 v[108:109], v[108:109], v[110:111]
	v_pk_add_f32 v[96:97], v[96:97], v[98:99]
	v_pk_add_f32 v[98:99], v[140:141], v[142:143]
	v_pk_add_f32 v[104:105], v[104:105], v[108:109]
	v_pk_add_f32 v[96:97], v[96:97], v[98:99]
	v_cvt_pk_bf16_f32 v100, v100, v101
	v_pk_add_f32 v[96:97], v[104:105], v[96:97]
	ds_bpermute_b32 v98, v148, v96
	ds_bpermute_b32 v99, v148, v97
	v_cvt_pk_bf16_f32 v101, v102, v103
	v_cvt_pk_bf16_f32 v117, v106, v107
	global_store_dwordx2 v[114:115], v[100:101], off offset:256
	v_cvt_pk_bf16_f32 v100, v126, v127
	s_waitcnt lgkmcnt(0)
	v_pk_add_f32 v[96:97], v[96:97], v[98:99]
	ds_bpermute_b32 v98, v149, v96
	ds_bpermute_b32 v99, v149, v97
	v_cvt_pk_bf16_f32 v101, v124, v125
	global_store_dwordx2 v[114:115], v[116:117], off offset:32
	global_store_dwordx2 v[114:115], v[100:101], off offset:288
	s_and_saveexec_b64 s[50:51], s[8:9]
	s_cbranch_execz .LBB0_1052
	s_waitcnt lgkmcnt(0)
	v_pk_add_f32 v[96:97], v[96:97], v[98:99]
	v_lshlrev_b64 v[98:99], 7, v[112:113]
	v_lshl_add_u64 v[98:99], s[24:25], 0, v[98:99]
	v_lshl_add_u64 v[98:99], s[14:15], 2, v[98:99]
	global_store_dwordx2 v[98:99], v[96:97], off
; #define GASP __attribute__((address_space(1)))
;     __device__ __forceinline__ void operator()(Acc& acc, const Unit& u, int wr, int wc, int fr, int fq, LAS unsigned char* lds) const {
;     ...
;                 const int rl = ai * HALF + wr * 64 + m * 16 + fr, row = u.pm * BM + rl;
;                 const float* rp = (row < split) ? res0 + (size_t)row * D : res1 + (size_t)(row - split) * D;
;                 float* op = out + (size_t)row * D;
;                 f32x2 st = (f32x2){0.f, 1.f}; if (STp) st = SL[rl];
;                 float s = 0.f, q = 0.f;
; #pragma unroll
;                 for (int bj = 0; bj < 2; ++bj)
; #pragma unroll
;                     for (int n = 0; n < 2; ++n) { const int c = col0 + bj * HALF + n * 16; f32x4 r;
;                         if (resb) { const u32x2 w = *(const GASP u32x2*)(resb + (size_t)row * D + c);
;                             r = (f32x4){__uint_as_float(w.x << 16), __uint_as_float(w.x & 0xffff0000u), __uint_as_float(w.y << 16), __uint_as_float(w.y & 0xffff0000u)}; }
;                         else r = *(const GASP f32x4*)(rp + c);
;                         if (STp) r = (r - st[0]) * st[1] * gg[bj][n] + bb[bj][n];
;                         const f32x4 o = r * ALPHA + acc[ai][bj][m][n] * scale;
;                         if (out) *(GASP f32x4*)(op + c) = o;
;                         if (ob) { u32x2 w; w.x = pk2(o[0], o[1]); w.y = pk2(o[2], o[3]); *(GASP u32x2*)(ob + (size_t)row * D + c) = w; }
;                         s += (o[0] + o[1]) + (o[2] + o[3]); q += (o[0] * o[0] + o[1] * o[1]) + (o[2] * o[2] + o[3] * o[3]); }
;                 if (STn) { s += __shfl_xor(s, 16); s += __shfl_xor(s, 32); q += __shfl_xor(q, 16); q += __shfl_xor(q, 32);
;                     if (fq == 0) *(GASP f32x2*)(STn + (size_t)row * 32 + (u.pn * 4 + wc) * 2) = (f32x2){s, q}; }
.LBB0_1052:
	s_or_b64 exec, exec, s[50:51]
	v_add_u32_e32 v96, s37, v191
	v_ashrrev_i32_e32 v97, 31, v96
	v_cmp_gt_i32_e32 vcc, s73, v96
	s_nop 1
	v_cndmask_b32_e32 v97, 0, v97, vcc
	s_waitcnt lgkmcnt(0)
	v_lshlrev_b64 v[98:99], 11, v[96:97]
	v_lshl_add_u64 v[98:99], s[42:43], 0, v[98:99]
	v_lshl_add_u64 v[98:99], v[174:175], 1, v[98:99]
	ds_read_b64 v[108:109], v192
	s_waitcnt vmcnt(14)
	v_lshlrev_b32_e32 v111, 16, v245
	v_and_b32_e32 v112, 0xffff0000, v245
	v_lshlrev_b32_e32 v120, 16, v247
	v_and_b32_e32 v121, 0xffff0000, v247
	v_lshlrev_b32_e32 v110, 16, v244
	v_and_b32_e32 v100, 0xffff0000, v244
	v_lshlrev_b32_e32 v118, 16, v246
	v_and_b32_e32 v119, 0xffff0000, v246
	v_lshlrev_b32_e32 v122, 16, v248
	v_and_b32_e32 v123, 0xffff0000, v248
	v_lshlrev_b32_e32 v124, 16, v249
	v_and_b32_e32 v125, 0xffff0000, v249
	s_waitcnt lgkmcnt(0)
	v_sub_f32_e32 v103, v112, v108
	v_sub_f32_e32 v102, v111, v108
	v_sub_f32_e32 v105, v121, v108
	v_sub_f32_e32 v104, v120, v108
	v_lshlrev_b32_e32 v126, 16, v250
	v_and_b32_e32 v127, 0xffff0000, v250
	v_lshlrev_b32_e32 v128, 16, v251
	v_and_b32_e32 v129, 0xffff0000, v251
	v_add_u32_e32 v250, s37, v195
	v_mov_b32_e32 v251, 0
	v_lshlrev_b64 v[250:251], 11, v[250:251]
	v_lshl_add_u64 v[250:251], s[42:43], 0, v[250:251]
	v_lshl_add_u64 v[250:251], v[174:175], 1, v[250:251]
	global_load_dwordx2 v[244:245], v[250:251], off
	global_load_dwordx2 v[246:247], v[250:251], off offset:32
	global_load_dwordx2 v[248:249], v[250:251], off offset:256
	global_load_dwordx2 v[250:251], v[250:251], off offset:288
	v_sub_f32_e32 v101, v100, v108
	v_sub_f32_e32 v100, v110, v108
	v_sub_f32_e32 v107, v119, v108
	v_sub_f32_e32 v106, v118, v108
	v_pk_mul_f32 v[102:103], v[108:109], v[102:103] op_sel:[1,0]
	v_pk_mul_f32 v[104:105], v[108:109], v[104:105] op_sel:[1,0]
	v_sub_f32_e32 v111, v125, v108
	v_sub_f32_e32 v110, v124, v108
	v_sub_f32_e32 v113, v123, v108
	v_sub_f32_e32 v112, v122, v108
	v_sub_f32_e32 v117, v127, v108
	v_sub_f32_e32 v116, v126, v108
	v_pk_mul_f32 v[100:101], v[108:109], v[100:101] op_sel:[1,0]
	v_pk_mul_f32 v[106:107], v[108:109], v[106:107] op_sel:[1,0]
	v_pk_fma_f32 v[102:103], v[78:79], v[102:103], v[66:67]
	v_pk_fma_f32 v[104:105], v[70:71], v[104:105], v[82:83]
	v_sub_f32_e32 v115, v129, v108
	v_sub_f32_e32 v114, v128, v108
	v_pk_mul_f32 v[112:113], v[108:109], v[112:113] op_sel:[1,0]
	v_pk_mul_f32 v[110:111], v[108:109], v[110:111] op_sel:[1,0]
	v_pk_mul_f32 v[116:117], v[108:109], v[116:117] op_sel:[1,0]
	v_pk_fma_f32 v[100:101], v[76:77], v[100:101], v[64:65]
	v_pk_fma_f32 v[106:107], v[68:69], v[106:107], v[80:81]
	v_pk_fma_f32 v[62:63], v[102:103], s[34:35], v[62:63] op_sel_hi:[1,0,1]
	v_cndmask_b32_e64 v103, v105, v121, s[10:11]
	v_cndmask_b32_e64 v102, v104, v120, s[10:11]
	v_pk_mul_f32 v[108:109], v[108:109], v[114:115] op_sel:[1,0]
	v_pk_fma_f32 v[110:111], v[74:75], v[110:111], v[86:87]
	v_pk_fma_f32 v[112:113], v[72:73], v[112:113], v[84:85]
	v_pk_fma_f32 v[114:115], v[88:89], v[116:117], v[92:93]
	v_pk_fma_f32 v[60:61], v[100:101], s[34:35], v[60:61] op_sel_hi:[1,0,1]
	v_cndmask_b32_e64 v101, v107, v119, s[10:11]
	v_cndmask_b32_e64 v100, v106, v118, s[10:11]
	v_pk_fma_f32 v[58:59], v[102:103], s[34:35], v[58:59] op_sel_hi:[1,0,1]
	v_cndmask_b32_e64 v104, v112, v122, s[10:11]
	v_cndmask_b32_e64 v106, v110, v124, s[10:11]
	v_cndmask_b32_e64 v110, v114, v126, s[10:11]
	v_cvt_pk_bf16_f32 v112, v60, v61
	v_add_f32_e32 v114, v60, v61
	v_mul_f32_e32 v119, v60, v60
	v_mul_f32_e32 v61, v61, v61
	v_pk_fma_f32 v[56:57], v[100:101], s[34:35], v[56:57] op_sel_hi:[1,0,1]
	v_mul_f32_e32 v60, v58, v58
	v_cndmask_b32_e64 v105, v113, v123, s[10:11]
	v_cvt_pk_bf16_f32 v113, v62, v63
	v_add_f32_e32 v116, v62, v63
	v_mul_f32_e32 v121, v62, v62
	v_mul_f32_e32 v63, v63, v63
	v_pk_fma_f32 v[122:123], v[58:59], v[58:59], v[60:61] op_sel_hi:[1,1,0]
	v_mov_b32_e32 v118, v56
	v_mov_b32_e32 v60, v57
	v_mov_b32_e32 v120, v58
	v_mov_b32_e32 v62, v59
	v_pk_fma_f32 v[108:109], v[90:91], v[108:109], v[94:95]
	v_cndmask_b32_e64 v107, v111, v125, s[10:11]
	v_cndmask_b32_e64 v111, v115, v127, s[10:11]
	v_cvt_pk_bf16_f32 v100, v56, v57
	v_mul_f32_e32 v115, v56, v56
	v_mul_f32_e32 v117, v57, v57
	v_pk_add_f32 v[56:57], v[118:119], v[60:61]
	v_pk_add_f32 v[60:61], v[120:121], v[62:63]
	v_pk_fma_f32 v[54:55], v[106:107], s[34:35], v[54:55] op_sel_hi:[1,0,1]
	v_pk_fma_f32 v[52:53], v[104:105], s[34:35], v[52:53] op_sel_hi:[1,0,1]
	v_cndmask_b32_e64 v109, v109, v129, s[10:11]
	v_cndmask_b32_e64 v108, v108, v128, s[10:11]
	v_pk_add_f32 v[56:57], v[56:57], v[60:61]
	v_pk_add_f32 v[60:61], v[114:115], v[116:117]
	v_mov_b32_e32 v165, v123
	global_store_dwordx2 v[98:99], v[112:113], off
	v_mul_f32_e32 v103, v52, v52
	v_mul_f32_e32 v105, v53, v53
	v_mul_f32_e32 v107, v54, v54
	v_mul_f32_e32 v113, v55, v55
	v_pk_fma_f32 v[108:109], v[108:109], s[34:35], v[50:51] op_sel_hi:[1,0,1]
	v_pk_fma_f32 v[110:111], v[110:111], s[34:35], v[48:49] op_sel_hi:[1,0,1]
	v_pk_add_f32 v[60:61], v[60:61], v[164:165]
	v_mov_b32_e32 v102, v52
	v_mov_b32_e32 v104, v53
	v_mov_b32_e32 v106, v54
	v_mov_b32_e32 v112, v55
	v_mul_f32_e32 v49, v110, v110
	v_mul_f32_e32 v51, v111, v111
	v_mul_f32_e32 v125, v108, v108
	v_mul_f32_e32 v127, v109, v109
	v_pk_add_f32 v[56:57], v[56:57], v[60:61]
	v_pk_add_f32 v[60:61], v[102:103], v[104:105]
	v_pk_add_f32 v[62:63], v[106:107], v[112:113]
	v_mov_b32_e32 v48, v110
	v_mov_b32_e32 v50, v111
	v_mov_b32_e32 v124, v108
	v_mov_b32_e32 v126, v109
	v_pk_add_f32 v[60:61], v[60:61], v[62:63]
	v_pk_add_f32 v[48:49], v[48:49], v[50:51]
	v_pk_add_f32 v[50:51], v[124:125], v[126:127]
	v_pk_add_f32 v[56:57], v[56:57], v[60:61]
	v_pk_add_f32 v[48:49], v[48:49], v[50:51]
	v_cvt_pk_bf16_f32 v52, v52, v53
	v_pk_add_f32 v[48:49], v[56:57], v[48:49]
	ds_bpermute_b32 v50, v148, v48
	ds_bpermute_b32 v51, v148, v49
	v_cvt_pk_bf16_f32 v53, v54, v55
	v_cvt_pk_bf16_f32 v101, v58, v59
	global_store_dwordx2 v[98:99], v[52:53], off offset:256
	v_cvt_pk_bf16_f32 v52, v110, v111
	s_waitcnt lgkmcnt(0)
	v_pk_add_f32 v[48:49], v[48:49], v[50:51]
	ds_bpermute_b32 v50, v149, v48
	ds_bpermute_b32 v51, v149, v49
	v_cvt_pk_bf16_f32 v53, v108, v109
	global_store_dwordx2 v[98:99], v[100:101], off offset:32
	global_store_dwordx2 v[98:99], v[52:53], off offset:288
	s_and_saveexec_b64 s[50:51], s[8:9]
	s_cbranch_execz .LBB0_1054
	s_waitcnt lgkmcnt(0)
	v_pk_add_f32 v[48:49], v[48:49], v[50:51]
	v_lshlrev_b64 v[50:51], 7, v[96:97]
	v_lshl_add_u64 v[50:51], s[24:25], 0, v[50:51]
	v_lshl_add_u64 v[50:51], s[14:15], 2, v[50:51]
	global_store_dwordx2 v[50:51], v[48:49], off
; #define GASP __attribute__((address_space(1)))
;     __device__ __forceinline__ void operator()(Acc& acc, const Unit& u, int wr, int wc, int fr, int fq, LAS unsigned char* lds) const {
;     ...
;                 const int rl = ai * HALF + wr * 64 + m * 16 + fr, row = u.pm * BM + rl;
;                 const float* rp = (row < split) ? res0 + (size_t)row * D : res1 + (size_t)(row - split) * D;
;                 float* op = out + (size_t)row * D;
;                 f32x2 st = (f32x2){0.f, 1.f}; if (STp) st = SL[rl];
;                 float s = 0.f, q = 0.f;
; #pragma unroll
;                 for (int bj = 0; bj < 2; ++bj)
; #pragma unroll
;                     for (int n = 0; n < 2; ++n) { const int c = col0 + bj * HALF + n * 16; f32x4 r;
;                         if (resb) { const u32x2 w = *(const GASP u32x2*)(resb + (size_t)row * D + c);
;                             r = (f32x4){__uint_as_float(w.x << 16), __uint_as_float(w.x & 0xffff0000u), __uint_as_float(w.y << 16), __uint_as_float(w.y & 0xffff0000u)}; }
;                         else r = *(const GASP f32x4*)(rp + c);
;                         if (STp) r = (r - st[0]) * st[1] * gg[bj][n] + bb[bj][n];
;                         const f32x4 o = r * ALPHA + acc[ai][bj][m][n] * scale;
;                         if (out) *(GASP f32x4*)(op + c) = o;
;                         if (ob) { u32x2 w; w.x = pk2(o[0], o[1]); w.y = pk2(o[2], o[3]); *(GASP u32x2*)(ob + (size_t)row * D + c) = w; }
;                         s += (o[0] + o[1]) + (o[2] + o[3]); q += (o[0] * o[0] + o[1] * o[1]) + (o[2] * o[2] + o[3] * o[3]); }
;                 if (STn) { s += __shfl_xor(s, 16); s += __shfl_xor(s, 32); q += __shfl_xor(q, 16); q += __shfl_xor(q, 32);
;                     if (fq == 0) *(GASP f32x2*)(STn + (size_t)row * 32 + (u.pn * 4 + wc) * 2) = (f32x2){s, q}; }
.LBB0_1054:
	s_or_b64 exec, exec, s[50:51]
	v_add_u32_e32 v48, s37, v193
	v_ashrrev_i32_e32 v49, 31, v48
	v_cmp_gt_i32_e32 vcc, s73, v48
	s_nop 1
	v_cndmask_b32_e32 v49, 0, v49, vcc
	s_waitcnt lgkmcnt(0)
	v_lshlrev_b64 v[50:51], 11, v[48:49]
	v_lshl_add_u64 v[50:51], s[42:43], 0, v[50:51]
	v_lshl_add_u64 v[50:51], v[174:175], 1, v[50:51]
	ds_read_b64 v[60:61], v194
	s_waitcnt vmcnt(14)
	v_lshlrev_b32_e32 v63, 16, v237
	v_and_b32_e32 v96, 0xffff0000, v237
	v_lshlrev_b32_e32 v104, 16, v239
	v_and_b32_e32 v105, 0xffff0000, v239
	v_lshlrev_b32_e32 v62, 16, v236
	v_and_b32_e32 v52, 0xffff0000, v236
	v_lshlrev_b32_e32 v102, 16, v238
	v_and_b32_e32 v103, 0xffff0000, v238
	v_lshlrev_b32_e32 v106, 16, v240
	v_and_b32_e32 v107, 0xffff0000, v240
	v_lshlrev_b32_e32 v108, 16, v241
	v_and_b32_e32 v109, 0xffff0000, v241
	s_waitcnt lgkmcnt(0)
	v_sub_f32_e32 v55, v96, v60
	v_sub_f32_e32 v54, v63, v60
	v_sub_f32_e32 v57, v105, v60
	v_sub_f32_e32 v56, v104, v60
	v_lshlrev_b32_e32 v110, 16, v242
	v_and_b32_e32 v111, 0xffff0000, v242
	v_lshlrev_b32_e32 v112, 16, v243
	v_and_b32_e32 v113, 0xffff0000, v243
	v_add_u32_e32 v242, s37, v197
	v_mov_b32_e32 v243, 0
	v_lshlrev_b64 v[242:243], 11, v[242:243]
	v_lshl_add_u64 v[242:243], s[42:43], 0, v[242:243]
	v_lshl_add_u64 v[242:243], v[174:175], 1, v[242:243]
	global_load_dwordx2 v[236:237], v[242:243], off
	global_load_dwordx2 v[238:239], v[242:243], off offset:32
	global_load_dwordx2 v[240:241], v[242:243], off offset:256
	global_load_dwordx2 v[242:243], v[242:243], off offset:288
	v_sub_f32_e32 v53, v52, v60
	v_sub_f32_e32 v52, v62, v60
	v_sub_f32_e32 v59, v103, v60
	v_sub_f32_e32 v58, v102, v60
	v_pk_mul_f32 v[54:55], v[60:61], v[54:55] op_sel:[1,0]
	v_pk_mul_f32 v[56:57], v[60:61], v[56:57] op_sel:[1,0]
	v_sub_f32_e32 v63, v109, v60
	v_sub_f32_e32 v62, v108, v60
	v_sub_f32_e32 v97, v107, v60
	v_sub_f32_e32 v96, v106, v60
	v_sub_f32_e32 v101, v111, v60
	v_sub_f32_e32 v100, v110, v60
	v_pk_mul_f32 v[52:53], v[60:61], v[52:53] op_sel:[1,0]
	v_pk_mul_f32 v[58:59], v[60:61], v[58:59] op_sel:[1,0]
	v_pk_fma_f32 v[54:55], v[78:79], v[54:55], v[66:67]
	v_pk_fma_f32 v[56:57], v[70:71], v[56:57], v[82:83]
	v_sub_f32_e32 v99, v113, v60
	v_sub_f32_e32 v98, v112, v60
	v_pk_mul_f32 v[96:97], v[60:61], v[96:97] op_sel:[1,0]
	v_pk_mul_f32 v[62:63], v[60:61], v[62:63] op_sel:[1,0]
	v_pk_mul_f32 v[100:101], v[60:61], v[100:101] op_sel:[1,0]
	v_pk_fma_f32 v[52:53], v[76:77], v[52:53], v[64:65]
	v_pk_fma_f32 v[58:59], v[68:69], v[58:59], v[80:81]
	v_pk_fma_f32 v[46:47], v[54:55], s[34:35], v[46:47] op_sel_hi:[1,0,1]
	v_cndmask_b32_e64 v55, v57, v105, s[10:11]
	v_cndmask_b32_e64 v54, v56, v104, s[10:11]
	v_pk_mul_f32 v[60:61], v[60:61], v[98:99] op_sel:[1,0]
	v_pk_fma_f32 v[62:63], v[74:75], v[62:63], v[86:87]
	v_pk_fma_f32 v[96:97], v[72:73], v[96:97], v[84:85]
	v_pk_fma_f32 v[98:99], v[88:89], v[100:101], v[92:93]
	v_pk_fma_f32 v[44:45], v[52:53], s[34:35], v[44:45] op_sel_hi:[1,0,1]
	v_cndmask_b32_e64 v53, v59, v103, s[10:11]
	v_cndmask_b32_e64 v52, v58, v102, s[10:11]
	v_pk_fma_f32 v[42:43], v[54:55], s[34:35], v[42:43] op_sel_hi:[1,0,1]
	v_cndmask_b32_e64 v56, v96, v106, s[10:11]
	v_cndmask_b32_e64 v58, v62, v108, s[10:11]
	v_cndmask_b32_e64 v62, v98, v110, s[10:11]
	v_cvt_pk_bf16_f32 v96, v44, v45
	v_add_f32_e32 v98, v44, v45
	v_mul_f32_e32 v103, v44, v44
	v_mul_f32_e32 v45, v45, v45
	v_pk_fma_f32 v[40:41], v[52:53], s[34:35], v[40:41] op_sel_hi:[1,0,1]
	v_mul_f32_e32 v44, v42, v42
	v_cndmask_b32_e64 v57, v97, v107, s[10:11]
	v_cvt_pk_bf16_f32 v97, v46, v47
	v_add_f32_e32 v100, v46, v47
	v_mul_f32_e32 v105, v46, v46
	v_mul_f32_e32 v47, v47, v47
	v_pk_fma_f32 v[106:107], v[42:43], v[42:43], v[44:45] op_sel_hi:[1,1,0]
	v_mov_b32_e32 v102, v40
	v_mov_b32_e32 v44, v41
	v_mov_b32_e32 v104, v42
	v_mov_b32_e32 v46, v43
	v_pk_fma_f32 v[60:61], v[90:91], v[60:61], v[94:95]
	v_cndmask_b32_e64 v59, v63, v109, s[10:11]
	v_cndmask_b32_e64 v63, v99, v111, s[10:11]
	v_cvt_pk_bf16_f32 v52, v40, v41
	v_mul_f32_e32 v99, v40, v40
	v_mul_f32_e32 v101, v41, v41
	v_pk_add_f32 v[40:41], v[102:103], v[44:45]
	v_pk_add_f32 v[44:45], v[104:105], v[46:47]
	v_pk_fma_f32 v[38:39], v[58:59], s[34:35], v[38:39] op_sel_hi:[1,0,1]
	v_pk_fma_f32 v[36:37], v[56:57], s[34:35], v[36:37] op_sel_hi:[1,0,1]
	v_cndmask_b32_e64 v61, v61, v113, s[10:11]
	v_cndmask_b32_e64 v60, v60, v112, s[10:11]
	v_pk_add_f32 v[40:41], v[40:41], v[44:45]
	v_pk_add_f32 v[44:45], v[98:99], v[100:101]
	v_mov_b32_e32 v165, v107
	global_store_dwordx2 v[50:51], v[96:97], off
	v_mul_f32_e32 v55, v36, v36
	v_mul_f32_e32 v57, v37, v37
	v_mul_f32_e32 v59, v38, v38
	v_mul_f32_e32 v97, v39, v39
	v_pk_fma_f32 v[60:61], v[60:61], s[34:35], v[34:35] op_sel_hi:[1,0,1]
	v_pk_fma_f32 v[62:63], v[62:63], s[34:35], v[32:33] op_sel_hi:[1,0,1]
	v_pk_add_f32 v[44:45], v[44:45], v[164:165]
	v_mov_b32_e32 v54, v36
	v_mov_b32_e32 v56, v37
	v_mov_b32_e32 v58, v38
	v_mov_b32_e32 v96, v39
	v_mul_f32_e32 v33, v62, v62
	v_mul_f32_e32 v35, v63, v63
	v_mul_f32_e32 v109, v60, v60
	v_mul_f32_e32 v111, v61, v61
	v_pk_add_f32 v[40:41], v[40:41], v[44:45]
	v_pk_add_f32 v[44:45], v[54:55], v[56:57]
	v_pk_add_f32 v[46:47], v[58:59], v[96:97]
	v_mov_b32_e32 v32, v62
	v_mov_b32_e32 v34, v63
	v_mov_b32_e32 v108, v60
	v_mov_b32_e32 v110, v61
	v_pk_add_f32 v[44:45], v[44:45], v[46:47]
	v_pk_add_f32 v[32:33], v[32:33], v[34:35]
	v_pk_add_f32 v[34:35], v[108:109], v[110:111]
	v_pk_add_f32 v[40:41], v[40:41], v[44:45]
	v_pk_add_f32 v[32:33], v[32:33], v[34:35]
	v_cvt_pk_bf16_f32 v36, v36, v37
	v_pk_add_f32 v[32:33], v[40:41], v[32:33]
	ds_bpermute_b32 v34, v148, v32
	ds_bpermute_b32 v35, v148, v33
	v_cvt_pk_bf16_f32 v37, v38, v39
	v_cvt_pk_bf16_f32 v53, v42, v43
	global_store_dwordx2 v[50:51], v[36:37], off offset:256
	v_cvt_pk_bf16_f32 v36, v62, v63
	s_waitcnt lgkmcnt(0)
	v_pk_add_f32 v[32:33], v[32:33], v[34:35]
	ds_bpermute_b32 v34, v149, v32
	ds_bpermute_b32 v35, v149, v33
	v_cvt_pk_bf16_f32 v37, v60, v61
	global_store_dwordx2 v[50:51], v[52:53], off offset:32
	global_store_dwordx2 v[50:51], v[36:37], off offset:288
	s_and_saveexec_b64 s[50:51], s[8:9]
	s_cbranch_execz .LBB0_1056
	s_waitcnt lgkmcnt(0)
	v_pk_add_f32 v[32:33], v[32:33], v[34:35]
	v_lshlrev_b64 v[34:35], 7, v[48:49]
	v_lshl_add_u64 v[34:35], s[24:25], 0, v[34:35]
	v_lshl_add_u64 v[34:35], s[14:15], 2, v[34:35]
	global_store_dwordx2 v[34:35], v[32:33], off
; #define GASP __attribute__((address_space(1)))
;     __device__ __forceinline__ void operator()(Acc& acc, const Unit& u, int wr, int wc, int fr, int fq, LAS unsigned char* lds) const {
;     ...
;                 const int rl = ai * HALF + wr * 64 + m * 16 + fr, row = u.pm * BM + rl;
;                 const float* rp = (row < split) ? res0 + (size_t)row * D : res1 + (size_t)(row - split) * D;
;                 float* op = out + (size_t)row * D;
;                 f32x2 st = (f32x2){0.f, 1.f}; if (STp) st = SL[rl];
;                 float s = 0.f, q = 0.f;
; #pragma unroll
;                 for (int bj = 0; bj < 2; ++bj)
; #pragma unroll
;                     for (int n = 0; n < 2; ++n) { const int c = col0 + bj * HALF + n * 16; f32x4 r;
;                         if (resb) { const u32x2 w = *(const GASP u32x2*)(resb + (size_t)row * D + c);
;                             r = (f32x4){__uint_as_float(w.x << 16), __uint_as_float(w.x & 0xffff0000u), __uint_as_float(w.y << 16), __uint_as_float(w.y & 0xffff0000u)}; }
;                         else r = *(const GASP f32x4*)(rp + c);
;                         if (STp) r = (r - st[0]) * st[1] * gg[bj][n] + bb[bj][n];
;                         const f32x4 o = r * ALPHA + acc[ai][bj][m][n] * scale;
;                         if (out) *(GASP f32x4*)(op + c) = o;
;                         if (ob) { u32x2 w; w.x = pk2(o[0], o[1]); w.y = pk2(o[2], o[3]); *(GASP u32x2*)(ob + (size_t)row * D + c) = w; }
;                         s += (o[0] + o[1]) + (o[2] + o[3]); q += (o[0] * o[0] + o[1] * o[1]) + (o[2] * o[2] + o[3] * o[3]); }
;                 if (STn) { s += __shfl_xor(s, 16); s += __shfl_xor(s, 32); q += __shfl_xor(q, 16); q += __shfl_xor(q, 32);
;                     if (fq == 0) *(GASP f32x2*)(STn + (size_t)row * 32 + (u.pn * 4 + wc) * 2) = (f32x2){s, q}; }
.LBB0_1056:
	s_or_b64 exec, exec, s[50:51]
	v_add_u32_e32 v32, s37, v195
	v_ashrrev_i32_e32 v33, 31, v32
	v_cmp_gt_i32_e32 vcc, s73, v32
	s_nop 1
	v_cndmask_b32_e32 v33, 0, v33, vcc
	s_waitcnt lgkmcnt(0)
	v_lshlrev_b64 v[34:35], 11, v[32:33]
	v_lshl_add_u64 v[34:35], s[42:43], 0, v[34:35]
	v_lshl_add_u64 v[34:35], v[174:175], 1, v[34:35]
	ds_read_b64 v[44:45], v196
	s_waitcnt vmcnt(14)
	v_lshlrev_b32_e32 v47, 16, v245
	v_and_b32_e32 v48, 0xffff0000, v245
	v_lshlrev_b32_e32 v56, 16, v247
	v_and_b32_e32 v57, 0xffff0000, v247
	v_lshlrev_b32_e32 v46, 16, v244
	v_and_b32_e32 v36, 0xffff0000, v244
	v_lshlrev_b32_e32 v54, 16, v246
	v_and_b32_e32 v55, 0xffff0000, v246
	v_lshlrev_b32_e32 v58, 16, v248
	v_and_b32_e32 v59, 0xffff0000, v248
	v_lshlrev_b32_e32 v60, 16, v249
	v_and_b32_e32 v61, 0xffff0000, v249
	s_waitcnt lgkmcnt(0)
	v_sub_f32_e32 v39, v48, v44
	v_sub_f32_e32 v38, v47, v44
	v_sub_f32_e32 v41, v57, v44
	v_sub_f32_e32 v40, v56, v44
	v_lshlrev_b32_e32 v62, 16, v250
	v_and_b32_e32 v63, 0xffff0000, v250
	v_lshlrev_b32_e32 v96, 16, v251
	v_and_b32_e32 v97, 0xffff0000, v251
	v_sub_f32_e32 v37, v36, v44
	v_sub_f32_e32 v36, v46, v44
	v_sub_f32_e32 v43, v55, v44
	v_sub_f32_e32 v42, v54, v44
	v_pk_mul_f32 v[38:39], v[44:45], v[38:39] op_sel:[1,0]
	v_pk_mul_f32 v[40:41], v[44:45], v[40:41] op_sel:[1,0]
	v_sub_f32_e32 v47, v61, v44
	v_sub_f32_e32 v46, v60, v44
	v_sub_f32_e32 v49, v59, v44
	v_sub_f32_e32 v48, v58, v44
	v_sub_f32_e32 v53, v63, v44
	v_sub_f32_e32 v52, v62, v44
	v_pk_mul_f32 v[36:37], v[44:45], v[36:37] op_sel:[1,0]
	v_pk_mul_f32 v[42:43], v[44:45], v[42:43] op_sel:[1,0]
	v_pk_fma_f32 v[38:39], v[78:79], v[38:39], v[66:67]
	v_pk_fma_f32 v[40:41], v[70:71], v[40:41], v[82:83]
	v_sub_f32_e32 v51, v97, v44
	v_sub_f32_e32 v50, v96, v44
	v_pk_mul_f32 v[48:49], v[44:45], v[48:49] op_sel:[1,0]
	v_pk_mul_f32 v[46:47], v[44:45], v[46:47] op_sel:[1,0]
	v_pk_mul_f32 v[52:53], v[44:45], v[52:53] op_sel:[1,0]
	v_pk_fma_f32 v[36:37], v[76:77], v[36:37], v[64:65]
	v_pk_fma_f32 v[42:43], v[68:69], v[42:43], v[80:81]
	v_pk_fma_f32 v[30:31], v[38:39], s[34:35], v[30:31] op_sel_hi:[1,0,1]
	v_cndmask_b32_e64 v39, v41, v57, s[10:11]
	v_cndmask_b32_e64 v38, v40, v56, s[10:11]
	v_pk_mul_f32 v[44:45], v[44:45], v[50:51] op_sel:[1,0]
	v_pk_fma_f32 v[46:47], v[74:75], v[46:47], v[86:87]
	v_pk_fma_f32 v[48:49], v[72:73], v[48:49], v[84:85]
	v_pk_fma_f32 v[50:51], v[88:89], v[52:53], v[92:93]
	v_pk_fma_f32 v[28:29], v[36:37], s[34:35], v[28:29] op_sel_hi:[1,0,1]
	v_cndmask_b32_e64 v37, v43, v55, s[10:11]
	v_cndmask_b32_e64 v36, v42, v54, s[10:11]
	v_pk_fma_f32 v[26:27], v[38:39], s[34:35], v[26:27] op_sel_hi:[1,0,1]
	v_cndmask_b32_e64 v40, v48, v58, s[10:11]
	v_cndmask_b32_e64 v42, v46, v60, s[10:11]
	v_cndmask_b32_e64 v46, v50, v62, s[10:11]
	v_cvt_pk_bf16_f32 v48, v28, v29
	v_add_f32_e32 v50, v28, v29
	v_mul_f32_e32 v55, v28, v28
	v_mul_f32_e32 v29, v29, v29
	v_pk_fma_f32 v[24:25], v[36:37], s[34:35], v[24:25] op_sel_hi:[1,0,1]
	v_mul_f32_e32 v28, v26, v26
	v_cndmask_b32_e64 v41, v49, v59, s[10:11]
	v_cvt_pk_bf16_f32 v49, v30, v31
	v_add_f32_e32 v52, v30, v31
	v_mul_f32_e32 v57, v30, v30
	v_mul_f32_e32 v31, v31, v31
	v_pk_fma_f32 v[58:59], v[26:27], v[26:27], v[28:29] op_sel_hi:[1,1,0]
	v_mov_b32_e32 v54, v24
	v_mov_b32_e32 v28, v25
	v_mov_b32_e32 v56, v26
	v_mov_b32_e32 v30, v27
	v_pk_fma_f32 v[44:45], v[90:91], v[44:45], v[94:95]
	v_cndmask_b32_e64 v43, v47, v61, s[10:11]
	v_cndmask_b32_e64 v47, v51, v63, s[10:11]
	v_cvt_pk_bf16_f32 v36, v24, v25
	v_mul_f32_e32 v51, v24, v24
	v_mul_f32_e32 v53, v25, v25
	v_pk_add_f32 v[24:25], v[54:55], v[28:29]
	v_pk_add_f32 v[28:29], v[56:57], v[30:31]
	v_pk_fma_f32 v[22:23], v[42:43], s[34:35], v[22:23] op_sel_hi:[1,0,1]
	v_pk_fma_f32 v[20:21], v[40:41], s[34:35], v[20:21] op_sel_hi:[1,0,1]
	v_cndmask_b32_e64 v45, v45, v97, s[10:11]
	v_cndmask_b32_e64 v44, v44, v96, s[10:11]
	v_pk_add_f32 v[24:25], v[24:25], v[28:29]
	v_pk_add_f32 v[28:29], v[50:51], v[52:53]
	v_mov_b32_e32 v165, v59
	global_store_dwordx2 v[34:35], v[48:49], off
	v_mul_f32_e32 v39, v20, v20
	v_mul_f32_e32 v41, v21, v21
	v_mul_f32_e32 v43, v22, v22
	v_mul_f32_e32 v49, v23, v23
	v_pk_fma_f32 v[44:45], v[44:45], s[34:35], v[18:19] op_sel_hi:[1,0,1]
	v_pk_fma_f32 v[46:47], v[46:47], s[34:35], v[16:17] op_sel_hi:[1,0,1]
	v_pk_add_f32 v[28:29], v[28:29], v[164:165]
	v_mov_b32_e32 v38, v20
	v_mov_b32_e32 v40, v21
	v_mov_b32_e32 v42, v22
	v_mov_b32_e32 v48, v23
	v_mul_f32_e32 v17, v46, v46
	v_mul_f32_e32 v19, v47, v47
	v_mul_f32_e32 v61, v44, v44
	v_mul_f32_e32 v63, v45, v45
	v_pk_add_f32 v[24:25], v[24:25], v[28:29]
	v_pk_add_f32 v[28:29], v[38:39], v[40:41]
	v_pk_add_f32 v[30:31], v[42:43], v[48:49]
	v_mov_b32_e32 v16, v46
	v_mov_b32_e32 v18, v47
	v_mov_b32_e32 v60, v44
	v_mov_b32_e32 v62, v45
	v_pk_add_f32 v[28:29], v[28:29], v[30:31]
	v_pk_add_f32 v[16:17], v[16:17], v[18:19]
	v_pk_add_f32 v[18:19], v[60:61], v[62:63]
	v_pk_add_f32 v[24:25], v[24:25], v[28:29]
	v_pk_add_f32 v[16:17], v[16:17], v[18:19]
	v_cvt_pk_bf16_f32 v20, v20, v21
	v_pk_add_f32 v[16:17], v[24:25], v[16:17]
	ds_bpermute_b32 v18, v148, v16
	ds_bpermute_b32 v19, v148, v17
	v_cvt_pk_bf16_f32 v21, v22, v23
	v_cvt_pk_bf16_f32 v37, v26, v27
	global_store_dwordx2 v[34:35], v[20:21], off offset:256
	v_cvt_pk_bf16_f32 v20, v46, v47
	s_waitcnt lgkmcnt(0)
	v_pk_add_f32 v[16:17], v[16:17], v[18:19]
	ds_bpermute_b32 v18, v149, v16
	ds_bpermute_b32 v19, v149, v17
	v_cvt_pk_bf16_f32 v21, v44, v45
	global_store_dwordx2 v[34:35], v[36:37], off offset:32
	global_store_dwordx2 v[34:35], v[20:21], off offset:288
	s_and_saveexec_b64 s[50:51], s[8:9]
	s_cbranch_execz .LBB0_1058
	s_waitcnt lgkmcnt(0)
	v_pk_add_f32 v[16:17], v[16:17], v[18:19]
	v_lshlrev_b64 v[18:19], 7, v[32:33]
	v_lshl_add_u64 v[18:19], s[24:25], 0, v[18:19]
	v_lshl_add_u64 v[18:19], s[14:15], 2, v[18:19]
	global_store_dwordx2 v[18:19], v[16:17], off
; #define GASP __attribute__((address_space(1)))
;     __device__ __forceinline__ void operator()(Acc& acc, const Unit& u, int wr, int wc, int fr, int fq, LAS unsigned char* lds) const {
;     ...
;                 const int rl = ai * HALF + wr * 64 + m * 16 + fr, row = u.pm * BM + rl;
;                 const float* rp = (row < split) ? res0 + (size_t)row * D : res1 + (size_t)(row - split) * D;
;                 float* op = out + (size_t)row * D;
;                 f32x2 st = (f32x2){0.f, 1.f}; if (STp) st = SL[rl];
;                 float s = 0.f, q = 0.f;
; #pragma unroll
;                 for (int bj = 0; bj < 2; ++bj)
; #pragma unroll
;                     for (int n = 0; n < 2; ++n) { const int c = col0 + bj * HALF + n * 16; f32x4 r;
;                         if (resb) { const u32x2 w = *(const GASP u32x2*)(resb + (size_t)row * D + c);
;                             r = (f32x4){__uint_as_float(w.x << 16), __uint_as_float(w.x & 0xffff0000u), __uint_as_float(w.y << 16), __uint_as_float(w.y & 0xffff0000u)}; }
;                         else r = *(const GASP f32x4*)(rp + c);
;                         if (STp) r = (r - st[0]) * st[1] * gg[bj][n] + bb[bj][n];
;                         const f32x4 o = r * ALPHA + acc[ai][bj][m][n] * scale;
;                         if (out) *(GASP f32x4*)(op + c) = o;
;                         if (ob) { u32x2 w; w.x = pk2(o[0], o[1]); w.y = pk2(o[2], o[3]); *(GASP u32x2*)(ob + (size_t)row * D + c) = w; }
;                         s += (o[0] + o[1]) + (o[2] + o[3]); q += (o[0] * o[0] + o[1] * o[1]) + (o[2] * o[2] + o[3] * o[3]); }
;                 if (STn) { s += __shfl_xor(s, 16); s += __shfl_xor(s, 32); q += __shfl_xor(q, 16); q += __shfl_xor(q, 32);
;                     if (fq == 0) *(GASP f32x2*)(STn + (size_t)row * 32 + (u.pn * 4 + wc) * 2) = (f32x2){s, q}; }
.LBB0_1058:
	s_or_b64 exec, exec, s[50:51]
	v_add_u32_e32 v16, s37, v197
	v_ashrrev_i32_e32 v17, 31, v16
	v_cmp_gt_i32_e32 vcc, s73, v16
	s_nop 1
	v_cndmask_b32_e32 v17, 0, v17, vcc
	s_waitcnt lgkmcnt(0)
	v_lshlrev_b64 v[18:19], 11, v[16:17]
	v_lshl_add_u64 v[18:19], s[42:43], 0, v[18:19]
	v_lshl_add_u64 v[18:19], v[174:175], 1, v[18:19]
	ds_read_b64 v[28:29], v198
	s_waitcnt vmcnt(10)
	v_lshlrev_b32_e32 v31, 16, v237
	v_and_b32_e32 v32, 0xffff0000, v237
	v_lshlrev_b32_e32 v40, 16, v239
	v_and_b32_e32 v41, 0xffff0000, v239
	v_lshlrev_b32_e32 v30, 16, v236
	v_and_b32_e32 v20, 0xffff0000, v236
	v_lshlrev_b32_e32 v38, 16, v238
	v_and_b32_e32 v39, 0xffff0000, v238
	v_lshlrev_b32_e32 v42, 16, v240
	v_and_b32_e32 v43, 0xffff0000, v240
	v_lshlrev_b32_e32 v44, 16, v241
	v_and_b32_e32 v45, 0xffff0000, v241
	s_waitcnt lgkmcnt(0)
	v_sub_f32_e32 v23, v32, v28
	v_sub_f32_e32 v22, v31, v28
	v_sub_f32_e32 v25, v41, v28
	v_sub_f32_e32 v24, v40, v28
	v_lshlrev_b32_e32 v46, 16, v242
	v_and_b32_e32 v47, 0xffff0000, v242
	v_lshlrev_b32_e32 v48, 16, v243
	v_and_b32_e32 v49, 0xffff0000, v243
	v_sub_f32_e32 v21, v20, v28
	v_sub_f32_e32 v20, v30, v28
	v_sub_f32_e32 v27, v39, v28
	v_sub_f32_e32 v26, v38, v28
	v_pk_mul_f32 v[22:23], v[28:29], v[22:23] op_sel:[1,0]
	v_pk_mul_f32 v[24:25], v[28:29], v[24:25] op_sel:[1,0]
	v_sub_f32_e32 v31, v45, v28
	v_sub_f32_e32 v30, v44, v28
	v_sub_f32_e32 v33, v43, v28
	v_sub_f32_e32 v32, v42, v28
	v_sub_f32_e32 v37, v47, v28
	v_sub_f32_e32 v36, v46, v28
	v_pk_mul_f32 v[20:21], v[28:29], v[20:21] op_sel:[1,0]
	v_pk_mul_f32 v[26:27], v[28:29], v[26:27] op_sel:[1,0]
	v_pk_fma_f32 v[22:23], v[78:79], v[22:23], v[66:67]
	v_pk_fma_f32 v[24:25], v[70:71], v[24:25], v[82:83]
	v_sub_f32_e32 v35, v49, v28
	v_sub_f32_e32 v34, v48, v28
	v_pk_mul_f32 v[32:33], v[28:29], v[32:33] op_sel:[1,0]
	v_pk_mul_f32 v[30:31], v[28:29], v[30:31] op_sel:[1,0]
	v_pk_mul_f32 v[36:37], v[28:29], v[36:37] op_sel:[1,0]
	v_pk_fma_f32 v[20:21], v[76:77], v[20:21], v[64:65]
	v_pk_fma_f32 v[26:27], v[68:69], v[26:27], v[80:81]
	v_pk_fma_f32 v[14:15], v[22:23], s[34:35], v[14:15] op_sel_hi:[1,0,1]
	v_cndmask_b32_e64 v23, v25, v41, s[10:11]
	v_cndmask_b32_e64 v22, v24, v40, s[10:11]
	v_pk_mul_f32 v[28:29], v[28:29], v[34:35] op_sel:[1,0]
	v_pk_fma_f32 v[30:31], v[74:75], v[30:31], v[86:87]
	v_pk_fma_f32 v[32:33], v[72:73], v[32:33], v[84:85]
	v_pk_fma_f32 v[34:35], v[88:89], v[36:37], v[92:93]
	v_pk_fma_f32 v[12:13], v[20:21], s[34:35], v[12:13] op_sel_hi:[1,0,1]
	v_cndmask_b32_e64 v21, v27, v39, s[10:11]
	v_cndmask_b32_e64 v20, v26, v38, s[10:11]
	v_pk_fma_f32 v[10:11], v[22:23], s[34:35], v[10:11] op_sel_hi:[1,0,1]
	v_cndmask_b32_e64 v24, v32, v42, s[10:11]
	v_cndmask_b32_e64 v26, v30, v44, s[10:11]
	v_cndmask_b32_e64 v30, v34, v46, s[10:11]
	v_cvt_pk_bf16_f32 v32, v12, v13
	v_add_f32_e32 v34, v12, v13
	v_mul_f32_e32 v39, v12, v12
	v_mul_f32_e32 v13, v13, v13
	v_pk_fma_f32 v[8:9], v[20:21], s[34:35], v[8:9] op_sel_hi:[1,0,1]
	v_mul_f32_e32 v12, v10, v10
	v_cndmask_b32_e64 v25, v33, v43, s[10:11]
	v_cvt_pk_bf16_f32 v33, v14, v15
	v_add_f32_e32 v36, v14, v15
	v_mul_f32_e32 v41, v14, v14
	v_mul_f32_e32 v15, v15, v15
	v_pk_fma_f32 v[42:43], v[10:11], v[10:11], v[12:13] op_sel_hi:[1,1,0]
	v_mov_b32_e32 v38, v8
	v_mov_b32_e32 v12, v9
	v_mov_b32_e32 v40, v10
	v_mov_b32_e32 v14, v11
	v_pk_fma_f32 v[28:29], v[90:91], v[28:29], v[94:95]
	v_cndmask_b32_e64 v27, v31, v45, s[10:11]
	v_cndmask_b32_e64 v31, v35, v47, s[10:11]
	v_cvt_pk_bf16_f32 v20, v8, v9
	v_mul_f32_e32 v35, v8, v8
	v_mul_f32_e32 v37, v9, v9
	v_pk_add_f32 v[8:9], v[38:39], v[12:13]
	v_pk_add_f32 v[12:13], v[40:41], v[14:15]
	v_pk_fma_f32 v[6:7], v[26:27], s[34:35], v[6:7] op_sel_hi:[1,0,1]
	v_pk_fma_f32 v[4:5], v[24:25], s[34:35], v[4:5] op_sel_hi:[1,0,1]
	v_cndmask_b32_e64 v29, v29, v49, s[10:11]
	v_cndmask_b32_e64 v28, v28, v48, s[10:11]
	v_pk_add_f32 v[8:9], v[8:9], v[12:13]
	v_pk_add_f32 v[12:13], v[34:35], v[36:37]
	v_mov_b32_e32 v165, v43
	global_store_dwordx2 v[18:19], v[32:33], off
	v_mul_f32_e32 v23, v4, v4
	v_mul_f32_e32 v25, v5, v5
	v_mul_f32_e32 v27, v6, v6
	v_mul_f32_e32 v33, v7, v7
	v_pk_fma_f32 v[28:29], v[28:29], s[34:35], v[2:3] op_sel_hi:[1,0,1]
	v_pk_fma_f32 v[30:31], v[30:31], s[34:35], v[0:1] op_sel_hi:[1,0,1]
	v_pk_add_f32 v[12:13], v[12:13], v[164:165]
	v_mov_b32_e32 v22, v4
	v_mov_b32_e32 v24, v5
	v_mov_b32_e32 v26, v6
	v_mov_b32_e32 v32, v7
	v_mul_f32_e32 v1, v30, v30
	v_mul_f32_e32 v3, v31, v31
	v_mul_f32_e32 v45, v28, v28
	v_mul_f32_e32 v47, v29, v29
	v_pk_add_f32 v[8:9], v[8:9], v[12:13]
	v_pk_add_f32 v[12:13], v[22:23], v[24:25]
	v_pk_add_f32 v[14:15], v[26:27], v[32:33]
	v_mov_b32_e32 v0, v30
	v_mov_b32_e32 v2, v31
	v_mov_b32_e32 v44, v28
	v_mov_b32_e32 v46, v29
	v_pk_add_f32 v[12:13], v[12:13], v[14:15]
	v_pk_add_f32 v[0:1], v[0:1], v[2:3]
	v_pk_add_f32 v[2:3], v[44:45], v[46:47]
	v_pk_add_f32 v[8:9], v[8:9], v[12:13]
	v_pk_add_f32 v[0:1], v[0:1], v[2:3]
	v_cvt_pk_bf16_f32 v4, v4, v5
	v_pk_add_f32 v[0:1], v[8:9], v[0:1]
	ds_bpermute_b32 v2, v148, v0
	ds_bpermute_b32 v3, v148, v1
	v_cvt_pk_bf16_f32 v5, v6, v7
	v_cvt_pk_bf16_f32 v21, v10, v11
	global_store_dwordx2 v[18:19], v[4:5], off offset:256
	v_cvt_pk_bf16_f32 v4, v30, v31
	s_waitcnt lgkmcnt(0)
	v_pk_add_f32 v[0:1], v[0:1], v[2:3]
	ds_bpermute_b32 v2, v149, v0
	ds_bpermute_b32 v3, v149, v1
	v_cvt_pk_bf16_f32 v5, v28, v29
	global_store_dwordx2 v[18:19], v[20:21], off offset:32
	global_store_dwordx2 v[18:19], v[4:5], off offset:288
	s_and_saveexec_b64 s[50:51], s[8:9]
	s_cbranch_execz .LBB0_1060
	s_waitcnt lgkmcnt(0)
	v_pk_add_f32 v[0:1], v[0:1], v[2:3]
	v_lshlrev_b64 v[2:3], 7, v[16:17]
	v_lshl_add_u64 v[2:3], s[24:25], 0, v[2:3]
	v_lshl_add_u64 v[2:3], s[14:15], 2, v[2:3]
	global_store_dwordx2 v[2:3], v[0:1], off
